# AddRes epilogues (both out-proj, FFN-down): the single vmcnt(0) after the 16 residual loads replaced by progressive counted waits vmcnt(15..0)
# speedup vs baseline: 1.0362x; 1.0019x over previous
; #define PG8_STAGE(bufoff, gbase, voff) do { _Pragma("unroll") for (int _i = 0; _i < 2; ++_i) \
;         __builtin_amdgcn_global_load_lds((const unsigned*)((const char*)(gbase) + (voff)[_i]), (LAS unsigned*)(lds + (bufoff) + ldsw + _i * 8192), 16, 0, 0); } while (0)
; #define PG8_LDA(dst, b, h) do { _Pragma("unroll") for (int m = 0; m < 4; ++m) _Pragma("unroll") for (int k = 0; k < 2; ++k) dst[m][k] = *(const LAS bf16x8*)(lds + PG8_SA(b, h) + aoff + m * 2048 + k * 1024); } while (0)
; #define PG8_LDB(dst, b, h) do { _Pragma("unroll") for (int n = 0; n < 2; ++n) _Pragma("unroll") for (int k = 0; k < 2; ++k) dst[n][k] = *(const LAS bf16x8*)(lds + PG8_SB(b, h) + boff + n * 2048 + k * 1024); } while (0)
; #define PG8_MMA(ai, bj, At, Bt) do { __builtin_amdgcn_s_setprio(1); _Pragma("unroll") for (int m = 0; m < 4; ++m) _Pragma("unroll") for (int n = 0; n < 2; ++n) _Pragma("unroll") for (int k = 0; k < 2; ++k) \
;         acc[ai][bj][m][n] = __builtin_amdgcn_mfma_f32_16x16x32_bf16(Bt[n][k], At[m][k], acc[ai][bj][m][n], 0, 0, 0); __builtin_amdgcn_s_setprio(0); } while (0)
; #define PG8_WAIT_V(n) asm volatile("s_waitcnt vmcnt(" #n ")" ::: "memory")
; #define PG8_BAR __builtin_amdgcn_s_barrier()
; template <class Epi, class Sched>
; __device__ __forceinline__ void gemm_phase(LAS unsigned char* lds, const Gemm g, const Sched& S, const Epi& E) {
;     ...
;         for (int t = 0; t < nt; t += 2) {
;             const bool last = (t == nt - 2);
;             const char* a1 = cA + (size_t)(t + 1) * kstep;
;             const char* a2 = last ? nA : cA + (size_t)(t + 2) * kstep; const char* b2 = last ? nB : cB + (size_t)(t + 2) * kstep;
;             const char* a3 = a2 + kstep; const char* b3 = b2 + kstep;
;             if (last && has_next) S.a_ready(nxt);
;             PG8_LDB(B0, 0, 0); PG8_SCHED; PG8_LDA(At, 0, 0); PG8_STAGE(PG8_SA(1, 1), a1 + hstepA, voffA);
;             PG8_WAIT_L(8); PG8_BAR; PG8_WAIT_L(0); PG8_MMA(0, 0, At, B0); PG8_BAR; PG8_SCHED;
;             PG8_LDB(B1, 0, 1); PG8_STAGE(PG8_SB(0, 0), b2, voffB);
;             PG8_BAR; PG8_WAIT_L(0); PG8_MMA(0, 1, At, B1); PG8_BAR;
;             PG8_LDA(At, 0, 1); PG8_STAGE(PG8_SA(0, 0), a2, voffA);
;             PG8_BAR; PG8_WAIT_L(0); PG8_MMA(1, 0, At, B0); PG8_BAR; PG8_SCHED;
;             PG8_STAGE(PG8_SB(0, 1), b2 + hstepB, voffB);
;             PG8_WAIT_V(6); PG8_BAR; PG8_MMA(1, 1, At, B1); PG8_BAR;
.LBB0_966:
	s_setprio 0
	s_add_u32 s20, s6, 0xfff80080
	s_addc_u32 s21, s7, -1
	s_add_i32 s52, 0, 0x10000
	v_add_u32_e32 v144, s52, v1
	ds_read_b128 v[132:135], v144
	ds_read_b128 v[136:139], v144 offset:1024
	ds_read_b128 v[140:143], v144 offset:2048
	ds_read_b128 v[144:147], v144 offset:3072
	s_cmp_eq_u32 s51, 28
	s_cselect_b32 s25, s15, s21
	s_cselect_b32 s24, s47, s20
	s_cselect_b32 s21, s1, s50
	s_cselect_b32 s20, s48, s49
	ds_read_b128 v[148:151], v224
	ds_read_b128 v[152:155], v224 offset:1024
	ds_read_b128 v[156:159], v224 offset:2048
	ds_read_b128 v[160:163], v224 offset:3072
	ds_read_b128 v[164:167], v224 offset:4096
	ds_read_b128 v[168:171], v224 offset:5120
	ds_read_b128 v[172:175], v224 offset:6144
	ds_read_b128 v[176:179], v224 offset:7168
	s_add_i32 s54, 0, 0x14000
	v_add_u32_e32 v202, s54, v1
	ds_read_b128 v[180:183], v202
	ds_read_b128 v[184:187], v202 offset:1024
	ds_read_b128 v[188:191], v202 offset:2048
	ds_read_b128 v[202:205], v202 offset:3072
	s_add_i32 m0, s31, 0xc000
	s_nop 0
	global_load_lds_dwordx4 v198, s[6:7]
	s_add_i32 m0, s31, 0xe000
	s_nop 0
	global_load_lds_dwordx4 v200, s[6:7]
	s_waitcnt lgkmcnt(0)
	s_setprio 1
	s_barrier
	v_mfma_f32_16x16x32_bf16 v[128:131], v[132:135], v[148:151], v[128:131]
	v_mfma_f32_16x16x32_bf16 v[124:127], v[140:143], v[148:151], v[124:127]
	v_mfma_f32_16x16x32_bf16 v[112:115], v[132:135], v[156:159], v[112:115]
	v_mfma_f32_16x16x32_bf16 v[108:111], v[140:143], v[156:159], v[108:111]
	v_mfma_f32_16x16x32_bf16 v[100:103], v[132:135], v[164:167], v[100:103]
	v_mfma_f32_16x16x32_bf16 v[92:95], v[140:143], v[164:167], v[92:95]
	v_mfma_f32_16x16x32_bf16 v[84:87], v[132:135], v[172:175], v[84:87]
	v_mfma_f32_16x16x32_bf16 v[76:79], v[140:143], v[172:175], v[76:79]
	v_mfma_f32_16x16x32_bf16 v[128:131], v[136:139], v[152:155], v[128:131]
	v_mfma_f32_16x16x32_bf16 v[124:127], v[144:147], v[152:155], v[124:127]
	v_mfma_f32_16x16x32_bf16 v[112:115], v[136:139], v[160:163], v[112:115]
	v_mfma_f32_16x16x32_bf16 v[108:111], v[144:147], v[160:163], v[108:111]
	v_mfma_f32_16x16x32_bf16 v[100:103], v[136:139], v[168:171], v[100:103]
	v_mfma_f32_16x16x32_bf16 v[92:95], v[144:147], v[168:171], v[92:95]
	v_mfma_f32_16x16x32_bf16 v[84:87], v[136:139], v[176:179], v[84:87]
	v_mfma_f32_16x16x32_bf16 v[76:79], v[144:147], v[176:179], v[76:79]
	v_mfma_f32_16x16x32_bf16 v[120:123], v[180:183], v[148:151], v[120:123]
	v_mfma_f32_16x16x32_bf16 v[116:119], v[188:191], v[148:151], v[116:119]
	v_mfma_f32_16x16x32_bf16 v[104:107], v[180:183], v[156:159], v[104:107]
	v_mfma_f32_16x16x32_bf16 v[96:99], v[188:191], v[156:159], v[96:99]
	v_mfma_f32_16x16x32_bf16 v[88:91], v[180:183], v[164:167], v[88:91]
	v_mfma_f32_16x16x32_bf16 v[80:83], v[188:191], v[164:167], v[80:83]
	v_mfma_f32_16x16x32_bf16 v[72:75], v[180:183], v[172:175], v[72:75]
	v_mfma_f32_16x16x32_bf16 v[68:71], v[188:191], v[172:175], v[68:71]
	v_mfma_f32_16x16x32_bf16 v[120:123], v[184:187], v[152:155], v[120:123]
	v_mfma_f32_16x16x32_bf16 v[116:119], v[202:205], v[152:155], v[116:119]
	v_mfma_f32_16x16x32_bf16 v[104:107], v[184:187], v[160:163], v[104:107]
	v_mfma_f32_16x16x32_bf16 v[96:99], v[202:205], v[160:163], v[96:99]
	v_mfma_f32_16x16x32_bf16 v[88:91], v[184:187], v[168:171], v[88:91]
	v_mfma_f32_16x16x32_bf16 v[80:83], v[202:205], v[168:171], v[80:83]
	v_mfma_f32_16x16x32_bf16 v[72:75], v[184:187], v[176:179], v[72:75]
	v_mfma_f32_16x16x32_bf16 v[68:71], v[202:205], v[176:179], v[68:71]
	s_barrier
	s_setprio 0
	ds_read_b128 v[148:151], v224 offset:16384
	ds_read_b128 v[152:155], v224 offset:17408
	ds_read_b128 v[156:159], v224 offset:18432
	ds_read_b128 v[160:163], v224 offset:19456
	ds_read_b128 v[164:167], v224 offset:20480
	ds_read_b128 v[168:171], v224 offset:21504
	ds_read_b128 v[172:175], v224 offset:22528
	ds_read_b128 v[176:179], v224 offset:23552
	s_add_i32 s52, s52, s30
	v_lshl_add_u64 v[206:207], s[20:21], 0, v[2:3]
	s_mov_b32 m0, s52
	s_nop 0
	global_load_lds_dwordx4 v[206:207], off
	v_lshl_add_u64 v[208:209], s[20:21], 0, v[192:193]
	s_add_i32 m0, s52, 0x2000
	s_nop 0
	global_load_lds_dwordx4 v[208:209], off
	s_mov_b32 m0, s31
	v_lshl_add_u64 v[210:211], s[24:25], 0, v[196:197]
	global_load_lds_dwordx4 v[210:211], off
	v_lshl_add_u64 v[212:213], s[24:25], 0, v[194:195]
	s_mov_b32 m0, s35
	s_nop 0
	global_load_lds_dwordx4 v[212:213], off
	s_add_u32 s52, s20, 0x80000
	s_addc_u32 s53, s21, 0
	s_add_i32 s54, s54, s30
	s_mov_b32 m0, s54
	s_nop 0
	global_load_lds_dwordx4 v2, s[52:53]
	s_add_i32 m0, s54, 0x2000
	s_nop 0
	global_load_lds_dwordx4 v192, s[52:53]
	s_waitcnt lgkmcnt(0)
	s_waitcnt vmcnt(6)
	s_setprio 1
	s_barrier
; #define PG8_STAGE(bufoff, gbase, voff) do { _Pragma("unroll") for (int _i = 0; _i < 2; ++_i) \
;         __builtin_amdgcn_global_load_lds((const unsigned*)((const char*)(gbase) + (voff)[_i]), (LAS unsigned*)(lds + (bufoff) + ldsw + _i * 8192), 16, 0, 0); } while (0)
; #define PG8_LDA(dst, b, h) do { _Pragma("unroll") for (int m = 0; m < 4; ++m) _Pragma("unroll") for (int k = 0; k < 2; ++k) dst[m][k] = *(const LAS bf16x8*)(lds + PG8_SA(b, h) + aoff + m * 2048 + k * 1024); } while (0)
; #define PG8_LDB(dst, b, h) do { _Pragma("unroll") for (int n = 0; n < 2; ++n) _Pragma("unroll") for (int k = 0; k < 2; ++k) dst[n][k] = *(const LAS bf16x8*)(lds + PG8_SB(b, h) + boff + n * 2048 + k * 1024); } while (0)
; #define PG8_MMA(ai, bj, At, Bt) do { __builtin_amdgcn_s_setprio(1); _Pragma("unroll") for (int m = 0; m < 4; ++m) _Pragma("unroll") for (int n = 0; n < 2; ++n) _Pragma("unroll") for (int k = 0; k < 2; ++k) \
;         acc[ai][bj][m][n] = __builtin_amdgcn_mfma_f32_16x16x32_bf16(Bt[n][k], At[m][k], acc[ai][bj][m][n], 0, 0, 0); __builtin_amdgcn_s_setprio(0); } while (0)
; #define PG8_WAIT_V(n) asm volatile("s_waitcnt vmcnt(" #n ")" ::: "memory")
; #define PG8_WAIT_L(n) asm volatile("s_waitcnt lgkmcnt(" #n ")" ::: "memory")
; #define PG8_BAR __builtin_amdgcn_s_barrier()
; #define PG8_SCHED __builtin_amdgcn_sched_barrier(0)
; template <class Epi, class Sched>
; __device__ __forceinline__ void gemm_phase(LAS unsigned char* lds, const Gemm g, const Sched& S, const Epi& E) {
;     ...
;             PG8_WAIT_V(6); PG8_BAR; PG8_MMA(1, 1, At, B1); PG8_BAR;
;             PG8_LDB(B0, 1, 0); PG8_SCHED; PG8_LDA(At, 1, 0); PG8_STAGE(PG8_SA(0, 1), a2 + hstepA, voffA);
;             PG8_WAIT_L(8); PG8_BAR; PG8_WAIT_L(0); PG8_MMA(0, 0, At, B0); PG8_BAR; PG8_SCHED;
;             PG8_LDB(B1, 1, 1); PG8_STAGE(PG8_SB(1, 0), b3, voffB);
;             PG8_BAR; PG8_WAIT_L(0); PG8_MMA(0, 1, At, B1); PG8_BAR;
;             PG8_LDA(At, 1, 1); PG8_STAGE(PG8_SA(1, 0), a3, voffA);
;             PG8_BAR; PG8_WAIT_L(0); PG8_MMA(1, 0, At, B0); PG8_BAR; PG8_SCHED;
	v_mfma_f32_16x16x32_bf16 v[64:67], v[132:135], v[148:151], v[64:67]
	v_mfma_f32_16x16x32_bf16 v[60:63], v[140:143], v[148:151], v[60:63]
	v_mfma_f32_16x16x32_bf16 v[52:55], v[132:135], v[156:159], v[52:55]
	v_mfma_f32_16x16x32_bf16 v[44:47], v[140:143], v[156:159], v[44:47]
	v_mfma_f32_16x16x32_bf16 v[36:39], v[132:135], v[164:167], v[36:39]
	v_mfma_f32_16x16x32_bf16 v[28:31], v[140:143], v[164:167], v[28:31]
	v_mfma_f32_16x16x32_bf16 v[20:23], v[132:135], v[172:175], v[20:23]
	v_mfma_f32_16x16x32_bf16 v[12:15], v[140:143], v[172:175], v[12:15]
	v_mfma_f32_16x16x32_bf16 v[64:67], v[136:139], v[152:155], v[64:67]
	v_mfma_f32_16x16x32_bf16 v[60:63], v[144:147], v[152:155], v[60:63]
	v_mfma_f32_16x16x32_bf16 v[52:55], v[136:139], v[160:163], v[52:55]
	v_mfma_f32_16x16x32_bf16 v[44:47], v[144:147], v[160:163], v[44:47]
	v_mfma_f32_16x16x32_bf16 v[36:39], v[136:139], v[168:171], v[36:39]
	v_mfma_f32_16x16x32_bf16 v[28:31], v[144:147], v[168:171], v[28:31]
	v_mfma_f32_16x16x32_bf16 v[20:23], v[136:139], v[176:179], v[20:23]
	v_mfma_f32_16x16x32_bf16 v[12:15], v[144:147], v[176:179], v[12:15]
	v_mfma_f32_16x16x32_bf16 v[56:59], v[180:183], v[148:151], v[56:59]
	v_mfma_f32_16x16x32_bf16 v[48:51], v[188:191], v[148:151], v[48:51]
	v_mfma_f32_16x16x32_bf16 v[40:43], v[180:183], v[156:159], v[40:43]
	v_mfma_f32_16x16x32_bf16 v[32:35], v[188:191], v[156:159], v[32:35]
	v_mfma_f32_16x16x32_bf16 v[24:27], v[180:183], v[164:167], v[24:27]
	v_mfma_f32_16x16x32_bf16 v[16:19], v[188:191], v[164:167], v[16:19]
	v_mfma_f32_16x16x32_bf16 v[8:11], v[180:183], v[172:175], v[8:11]
	v_mfma_f32_16x16x32_bf16 v[4:7], v[188:191], v[172:175], v[4:7]
	v_mfma_f32_16x16x32_bf16 v[56:59], v[184:187], v[152:155], v[56:59]
	v_mfma_f32_16x16x32_bf16 v[48:51], v[202:205], v[152:155], v[48:51]
	v_mfma_f32_16x16x32_bf16 v[40:43], v[184:187], v[160:163], v[40:43]
	v_mfma_f32_16x16x32_bf16 v[32:35], v[202:205], v[160:163], v[32:35]
	v_mfma_f32_16x16x32_bf16 v[24:27], v[184:187], v[168:171], v[24:27]
	v_mfma_f32_16x16x32_bf16 v[16:19], v[202:205], v[168:171], v[16:19]
	v_mfma_f32_16x16x32_bf16 v[8:11], v[184:187], v[176:179], v[8:11]
	v_mfma_f32_16x16x32_bf16 v[4:7], v[202:205], v[176:179], v[4:7]
	s_barrier
	s_setprio 0
	s_add_i32 s52, 0, 0x18000
	v_add_u32_e32 v144, s52, v1
	ds_read_b128 v[132:135], v144
	ds_read_b128 v[136:139], v144 offset:1024
	ds_read_b128 v[140:143], v144 offset:2048
	ds_read_b128 v[144:147], v144 offset:3072
	s_add_u32 s24, s24, 0x80000
	s_addc_u32 s25, s25, 0
	ds_read_b128 v[148:151], v224 offset:32768
	ds_read_b128 v[152:155], v224 offset:33792
	ds_read_b128 v[156:159], v224 offset:34816
	ds_read_b128 v[160:163], v224 offset:35840
	ds_read_b128 v[164:167], v224 offset:36864
	ds_read_b128 v[168:171], v224 offset:37888
	ds_read_b128 v[172:175], v224 offset:38912
	ds_read_b128 v[176:179], v224 offset:39936
	s_mov_b32 m0, s36
	s_nop 0
	global_load_lds_dwordx4 v196, s[24:25]
	s_mov_b32 m0, s37
	s_nop 0
	global_load_lds_dwordx4 v194, s[24:25]
	s_add_i32 s24, 0, 0x1c000
	v_add_u32_e32 v202, s24, v1
	ds_read_b128 v[180:183], v202
	ds_read_b128 v[184:187], v202 offset:1024
	ds_read_b128 v[188:191], v202 offset:2048
	ds_read_b128 v[202:205], v202 offset:3072
	s_waitcnt lgkmcnt(0)
	s_setprio 1
	s_barrier
	v_mfma_f32_16x16x32_bf16 v[128:131], v[132:135], v[148:151], v[128:131]
	v_mfma_f32_16x16x32_bf16 v[124:127], v[140:143], v[148:151], v[124:127]
	v_mfma_f32_16x16x32_bf16 v[112:115], v[132:135], v[156:159], v[112:115]
	v_mfma_f32_16x16x32_bf16 v[108:111], v[140:143], v[156:159], v[108:111]
	v_mfma_f32_16x16x32_bf16 v[100:103], v[132:135], v[164:167], v[100:103]
	v_mfma_f32_16x16x32_bf16 v[92:95], v[140:143], v[164:167], v[92:95]
	v_mfma_f32_16x16x32_bf16 v[84:87], v[132:135], v[172:175], v[84:87]
	v_mfma_f32_16x16x32_bf16 v[76:79], v[140:143], v[172:175], v[76:79]
	v_mfma_f32_16x16x32_bf16 v[128:131], v[136:139], v[152:155], v[128:131]
	v_mfma_f32_16x16x32_bf16 v[124:127], v[144:147], v[152:155], v[124:127]
	v_mfma_f32_16x16x32_bf16 v[112:115], v[136:139], v[160:163], v[112:115]
	v_mfma_f32_16x16x32_bf16 v[108:111], v[144:147], v[160:163], v[108:111]
	v_mfma_f32_16x16x32_bf16 v[100:103], v[136:139], v[168:171], v[100:103]
	v_mfma_f32_16x16x32_bf16 v[92:95], v[144:147], v[168:171], v[92:95]
	v_mfma_f32_16x16x32_bf16 v[84:87], v[136:139], v[176:179], v[84:87]
	v_mfma_f32_16x16x32_bf16 v[76:79], v[144:147], v[176:179], v[76:79]
	v_mfma_f32_16x16x32_bf16 v[120:123], v[180:183], v[148:151], v[120:123]
	v_mfma_f32_16x16x32_bf16 v[116:119], v[188:191], v[148:151], v[116:119]
	v_mfma_f32_16x16x32_bf16 v[104:107], v[180:183], v[156:159], v[104:107]
	v_mfma_f32_16x16x32_bf16 v[96:99], v[188:191], v[156:159], v[96:99]
	v_mfma_f32_16x16x32_bf16 v[88:91], v[180:183], v[164:167], v[88:91]
	v_mfma_f32_16x16x32_bf16 v[80:83], v[188:191], v[164:167], v[80:83]
	v_mfma_f32_16x16x32_bf16 v[72:75], v[180:183], v[172:175], v[72:75]
	v_mfma_f32_16x16x32_bf16 v[68:71], v[188:191], v[172:175], v[68:71]
	v_mfma_f32_16x16x32_bf16 v[120:123], v[184:187], v[152:155], v[120:123]
	v_mfma_f32_16x16x32_bf16 v[116:119], v[202:205], v[152:155], v[116:119]
	v_mfma_f32_16x16x32_bf16 v[104:107], v[184:187], v[160:163], v[104:107]
	v_mfma_f32_16x16x32_bf16 v[96:99], v[202:205], v[160:163], v[96:99]
	v_mfma_f32_16x16x32_bf16 v[88:91], v[184:187], v[168:171], v[88:91]
	v_mfma_f32_16x16x32_bf16 v[80:83], v[202:205], v[168:171], v[80:83]
	v_mfma_f32_16x16x32_bf16 v[72:75], v[184:187], v[176:179], v[72:75]
	v_mfma_f32_16x16x32_bf16 v[68:71], v[202:205], v[176:179], v[68:71]
	s_barrier
; __device__ __forceinline__ int opaque_tid() { int t = threadIdx.x; asm volatile("" : "+v"(t)); return t; }
; #define PG8_STAGE(bufoff, gbase, voff) do { _Pragma("unroll") for (int _i = 0; _i < 2; ++_i) \
;         __builtin_amdgcn_global_load_lds((const unsigned*)((const char*)(gbase) + (voff)[_i]), (LAS unsigned*)(lds + (bufoff) + ldsw + _i * 8192), 16, 0, 0); } while (0)
; #define PG8_LDA(dst, b, h) do { _Pragma("unroll") for (int m = 0; m < 4; ++m) _Pragma("unroll") for (int k = 0; k < 2; ++k) dst[m][k] = *(const LAS bf16x8*)(lds + PG8_SA(b, h) + aoff + m * 2048 + k * 1024); } while (0)
; #define PG8_MMA(ai, bj, At, Bt) do { __builtin_amdgcn_s_setprio(1); _Pragma("unroll") for (int m = 0; m < 4; ++m) _Pragma("unroll") for (int n = 0; n < 2; ++n) _Pragma("unroll") for (int k = 0; k < 2; ++k) \
;         acc[ai][bj][m][n] = __builtin_amdgcn_mfma_f32_16x16x32_bf16(Bt[n][k], At[m][k], acc[ai][bj][m][n], 0, 0, 0); __builtin_amdgcn_s_setprio(0); } while (0)
; #define PG8_WAIT_V(n) asm volatile("s_waitcnt vmcnt(" #n ")" ::: "memory")
; #define PG8_WAIT_L(n) asm volatile("s_waitcnt lgkmcnt(" #n ")" ::: "memory")
; #define PG8_BAR __builtin_amdgcn_s_barrier()
; #define PG8_SCHED __builtin_amdgcn_sched_barrier(0)
;     __device__ __forceinline__ void operator()(const f32x4 (&acc)[2][2][4][2], const Unit& u, int wr, int wc, int, int) const {
;         const int ol_ = opaque_tid() & 63, fr = ol_ & 15, fq = ol_ >> 4;
;         const int row0 = u.pm * BM + wr * 64 + fr, col0 = u.pn * BM + wc * 32 + 8 * fq;
;         u32x4 cin[2][4][2];
; #pragma unroll
;         for (int ai = 0; ai < 2; ++ai)
; #pragma unroll
;             for (int m = 0; m < 4; ++m)
; #pragma unroll
;                 for (int bj = 0; bj < 2; ++bj) cin[ai][m][bj] = *(const u32x4*)(C + (size_t)(row0 + ai * HALF + m * 16) * ldc + col0 + bj * HALF);
; template <class Epi, class Sched>
; __device__ __forceinline__ void gemm_phase(LAS unsigned char* lds, const Gemm g, const Sched& S, const Epi& E) {
;     ...
;             PG8_LDA(At, 1, 1); PG8_STAGE(PG8_SA(1, 0), a3, voffA);
;             PG8_BAR; PG8_WAIT_L(0); PG8_MMA(1, 0, At, B0); PG8_BAR; PG8_SCHED;
;             PG8_STAGE(PG8_SB(1, 1), b3 + hstepB, voffB);
;             PG8_WAIT_V(6); PG8_BAR; PG8_MMA(1, 1, At, B1); PG8_BAR;
	s_setprio 0
	ds_read_b128 v[148:151], v224 offset:49152
	ds_read_b128 v[152:155], v224 offset:50176
	ds_read_b128 v[156:159], v224 offset:51200
	ds_read_b128 v[160:163], v224 offset:52224
	ds_read_b128 v[164:167], v224 offset:53248
	ds_read_b128 v[168:171], v224 offset:54272
	ds_read_b128 v[172:175], v224 offset:55296
	ds_read_b128 v[176:179], v224 offset:56320
	s_add_i32 s25, s52, s30
	v_lshl_add_u64 v[206:207], v[206:207], 0, s[8:9]
	s_mov_b32 m0, s25
	s_nop 0
	global_load_lds_dwordx4 v[206:207], off
	v_lshl_add_u64 v[206:207], v[208:209], 0, s[8:9]
	s_add_i32 m0, s25, 0x2000
	s_nop 0
	global_load_lds_dwordx4 v[206:207], off
	s_mov_b32 m0, s40
	v_lshl_add_u64 v[206:207], v[210:211], 0, s[8:9]
	global_load_lds_dwordx4 v[206:207], off
	v_lshl_add_u64 v[206:207], v[212:213], 0, s[8:9]
	s_mov_b32 m0, s41
	s_nop 0
	global_load_lds_dwordx4 v[206:207], off
	s_add_u32 s20, s20, 0x80080
	s_addc_u32 s21, s21, 0
	s_add_i32 s24, s24, s30
	s_mov_b32 m0, s24
	s_nop 0
	global_load_lds_dwordx4 v2, s[20:21]
	s_add_i32 m0, s24, 0x2000
	s_nop 0
	global_load_lds_dwordx4 v192, s[20:21]
	s_add_i32 s51, s51, 2
	s_add_u32 s6, s6, 0x100
	s_addc_u32 s7, s7, 0
	s_add_u32 s49, s49, 0x100
	s_addc_u32 s50, s50, 0
	s_cmp_gt_u32 s51, 29
	s_waitcnt lgkmcnt(0)
	s_waitcnt vmcnt(6)
	s_setprio 1
	s_barrier
	v_mfma_f32_16x16x32_bf16 v[64:67], v[132:135], v[148:151], v[64:67]
	v_mfma_f32_16x16x32_bf16 v[60:63], v[140:143], v[148:151], v[60:63]
	v_mfma_f32_16x16x32_bf16 v[52:55], v[132:135], v[156:159], v[52:55]
	v_mfma_f32_16x16x32_bf16 v[44:47], v[140:143], v[156:159], v[44:47]
	v_mfma_f32_16x16x32_bf16 v[36:39], v[132:135], v[164:167], v[36:39]
	v_mfma_f32_16x16x32_bf16 v[28:31], v[140:143], v[164:167], v[28:31]
	v_mfma_f32_16x16x32_bf16 v[20:23], v[132:135], v[172:175], v[20:23]
	v_mfma_f32_16x16x32_bf16 v[12:15], v[140:143], v[172:175], v[12:15]
	v_mfma_f32_16x16x32_bf16 v[64:67], v[136:139], v[152:155], v[64:67]
	v_mfma_f32_16x16x32_bf16 v[60:63], v[144:147], v[152:155], v[60:63]
	v_mfma_f32_16x16x32_bf16 v[52:55], v[136:139], v[160:163], v[52:55]
	v_mfma_f32_16x16x32_bf16 v[44:47], v[144:147], v[160:163], v[44:47]
	v_mfma_f32_16x16x32_bf16 v[36:39], v[136:139], v[168:171], v[36:39]
	v_mfma_f32_16x16x32_bf16 v[28:31], v[144:147], v[168:171], v[28:31]
	v_mfma_f32_16x16x32_bf16 v[20:23], v[136:139], v[176:179], v[20:23]
	v_mfma_f32_16x16x32_bf16 v[12:15], v[144:147], v[176:179], v[12:15]
	v_mfma_f32_16x16x32_bf16 v[56:59], v[180:183], v[148:151], v[56:59]
	v_mfma_f32_16x16x32_bf16 v[48:51], v[188:191], v[148:151], v[48:51]
	v_mfma_f32_16x16x32_bf16 v[40:43], v[180:183], v[156:159], v[40:43]
	v_mfma_f32_16x16x32_bf16 v[32:35], v[188:191], v[156:159], v[32:35]
	v_mfma_f32_16x16x32_bf16 v[24:27], v[180:183], v[164:167], v[24:27]
	v_mfma_f32_16x16x32_bf16 v[16:19], v[188:191], v[164:167], v[16:19]
	v_mfma_f32_16x16x32_bf16 v[8:11], v[180:183], v[172:175], v[8:11]
	v_mfma_f32_16x16x32_bf16 v[4:7], v[188:191], v[172:175], v[4:7]
	v_mfma_f32_16x16x32_bf16 v[56:59], v[184:187], v[152:155], v[56:59]
	v_mfma_f32_16x16x32_bf16 v[48:51], v[202:205], v[152:155], v[48:51]
	v_mfma_f32_16x16x32_bf16 v[40:43], v[184:187], v[160:163], v[40:43]
	v_mfma_f32_16x16x32_bf16 v[32:35], v[202:205], v[160:163], v[32:35]
	v_mfma_f32_16x16x32_bf16 v[24:27], v[184:187], v[168:171], v[24:27]
	v_mfma_f32_16x16x32_bf16 v[16:19], v[202:205], v[168:171], v[16:19]
	v_mfma_f32_16x16x32_bf16 v[8:11], v[184:187], v[176:179], v[8:11]
	v_mfma_f32_16x16x32_bf16 v[4:7], v[202:205], v[176:179], v[4:7]
	s_barrier
	s_cbranch_scc0 .LBB0_966
	s_setprio 0
	v_mov_b32_e32 v133, v0
	s_lshl_b32 s1, s46, 8
	s_add_i32 s1, s1, s38
	v_and_or_b32 v132, v133, 15, s1
	s_lshl_b32 s1, s45, 8
	v_lshrrev_b32_e32 v133, 1, v133
	v_and_or_b32 v133, v133, 24, s1
	v_or_b32_e32 v134, s39, v133
	v_ashrrev_i32_e32 v135, 31, v134
	v_lshlrev_b64 v[202:203], 1, v[134:135]
	v_ashrrev_i32_e32 v133, 31, v132
	v_lshl_add_u64 v[134:135], s[88:89], 0, v[202:203]
	v_lshlrev_b64 v[226:227], 12, v[132:133]
	v_lshl_add_u64 v[136:137], v[134:135], 0, v[226:227]
	global_load_dwordx4 v[216:219], v[136:137], off
	global_load_dwordx4 v[188:191], v[136:137], off offset:256
	v_or_b32_e32 v136, 16, v132
	v_ashrrev_i32_e32 v137, 31, v136
	v_lshlrev_b64 v[222:223], 12, v[136:137]
	v_lshl_add_u64 v[136:137], v[134:135], 0, v[222:223]
	global_load_dwordx4 v[184:187], v[136:137], off
	global_load_dwordx4 v[180:183], v[136:137], off offset:256
	v_or_b32_e32 v136, 32, v132
	v_ashrrev_i32_e32 v137, 31, v136
	v_lshlrev_b64 v[220:221], 12, v[136:137]
	v_lshl_add_u64 v[136:137], v[134:135], 0, v[220:221]
	global_load_dwordx4 v[176:179], v[136:137], off
	global_load_dwordx4 v[168:171], v[136:137], off offset:256
	v_or_b32_e32 v132, 48, v132
	v_ashrrev_i32_e32 v133, 31, v132
	v_lshlrev_b64 v[212:213], 12, v[132:133]
	v_lshl_add_u64 v[132:133], v[134:135], 0, v[212:213]
	global_load_dwordx4 v[172:175], v[132:133], off
	global_load_dwordx4 v[164:167], v[132:133], off offset:256
	s_mov_b64 s[6:7], 0x80000
	v_lshl_add_u64 v[210:211], v[226:227], 0, s[6:7]
	v_lshl_add_u64 v[132:133], v[134:135], 0, v[210:211]
	global_load_dwordx4 v[160:163], v[132:133], off
	global_load_dwordx4 v[156:159], v[132:133], off offset:256
	s_mov_b64 s[6:7], 0x90000
	v_lshl_add_u64 v[208:209], v[226:227], 0, s[6:7]
	v_lshl_add_u64 v[132:133], v[134:135], 0, v[208:209]
	global_load_dwordx4 v[152:155], v[132:133], off
	global_load_dwordx4 v[148:151], v[132:133], off offset:256
	s_mov_b64 s[6:7], 0xa0000
	v_lshl_add_u64 v[206:207], v[226:227], 0, s[6:7]
	v_lshl_add_u64 v[132:133], v[134:135], 0, v[206:207]
	global_load_dwordx4 v[144:147], v[132:133], off
	global_load_dwordx4 v[140:143], v[132:133], off offset:256
	s_mov_b64 s[6:7], 0xb0000
	v_lshl_add_u64 v[204:205], v[226:227], 0, s[6:7]
	v_lshl_add_u64 v[132:133], v[134:135], 0, v[204:205]
	global_load_dwordx4 v[136:139], v[132:133], off
	s_nop 0
	global_load_dwordx4 v[132:135], v[132:133], off offset:256
	s_and_b64 vcc, exec, s[42:43]
	s_mov_b32 s45, s0
	s_mov_b32 s46, s14
	s_mov_b64 s[20:21], s[18:19]
	s_mov_b64 s[6:7], s[4:5]
	s_waitcnt vmcnt(15)
; __device__ __forceinline__ unsigned cvt_pk_bf16(float lo, float hi) { const f32x2 v = {lo, hi}; const bf16v2_ r = __builtin_convertvector(v, bf16v2_); return __builtin_bit_cast(unsigned, r); }
; __device__ __forceinline__ float bflo(unsigned w) { return __uint_as_float(w << 16); }
; __device__ __forceinline__ float bfhi(unsigned w) { return __uint_as_float(w & 0xffff0000u); }
;     __device__ __forceinline__ void operator()(const f32x4 (&acc)[2][2][4][2], const Unit& u, int wr, int wc, int, int) const {
;     ...
; #pragma unroll
;         for (int ai = 0; ai < 2; ++ai)
; #pragma unroll
;             for (int m = 0; m < 4; ++m)
; #pragma unroll
;                 for (int bj = 0; bj < 2; ++bj) { const u32x4 c = cin[ai][m][bj]; const f32x4 v0 = acc[ai][bj][m][0], v1 = acc[ai][bj][m][1];
;                     u32x4 w; w.x = cvt_pk_bf16(bflo(c.x) + v0[0], bfhi(c.x) + v0[1]); w.y = cvt_pk_bf16(bflo(c.y) + v0[2], bfhi(c.y) + v0[3]);
;                     w.z = cvt_pk_bf16(bflo(c.z) + v1[0], bfhi(c.z) + v1[1]); w.w = cvt_pk_bf16(bflo(c.w) + v1[2], bfhi(c.w) + v1[3]);
;                     *(u32x4*)(C + (size_t)(row0 + ai * HALF + m * 16) * ldc + col0 + bj * HALF) = w; }
	v_lshlrev_b32_e32 v228, 16, v216
	v_and_b32_e32 v229, 0xffff0000, v216
	v_lshlrev_b32_e32 v216, 16, v217
	v_and_b32_e32 v217, 0xffff0000, v217
	v_pk_add_f32 v[128:129], v[128:129], v[228:229]
	v_pk_add_f32 v[130:131], v[130:131], v[216:217]
	v_cvt_pk_bf16_f32 v128, v128, v129
	v_cvt_pk_bf16_f32 v129, v130, v131
	v_lshlrev_b32_e32 v130, 16, v218
	v_and_b32_e32 v131, 0xffff0000, v218
	v_pk_add_f32 v[124:125], v[124:125], v[130:131]
	s_nop 0
	v_cvt_pk_bf16_f32 v130, v124, v125
	v_lshlrev_b32_e32 v124, 16, v219
	v_and_b32_e32 v125, 0xffff0000, v219
	v_pk_add_f32 v[124:125], v[126:127], v[124:125]
	s_waitcnt vmcnt(14)
	v_lshlrev_b32_e32 v126, 16, v188
	v_and_b32_e32 v127, 0xffff0000, v188
	v_pk_add_f32 v[120:121], v[120:121], v[126:127]
	v_lshlrev_b32_e32 v126, 16, v189
	v_and_b32_e32 v127, 0xffff0000, v189
	v_pk_add_f32 v[122:123], v[122:123], v[126:127]
	v_cvt_pk_bf16_f32 v120, v120, v121
	v_cvt_pk_bf16_f32 v121, v122, v123
	v_lshlrev_b32_e32 v122, 16, v190
	v_and_b32_e32 v123, 0xffff0000, v190
	v_pk_add_f32 v[116:117], v[116:117], v[122:123]
	v_cvt_pk_bf16_f32 v131, v124, v125
	v_cvt_pk_bf16_f32 v122, v116, v117
	v_lshlrev_b32_e32 v116, 16, v191
	v_and_b32_e32 v117, 0xffff0000, v191
	v_pk_add_f32 v[116:117], v[118:119], v[116:117]
	v_lshl_add_u64 v[124:125], s[88:89], 0, v[226:227]
	v_cvt_pk_bf16_f32 v123, v116, v117
	s_waitcnt vmcnt(13)
	v_lshlrev_b32_e32 v116, 16, v184
	v_and_b32_e32 v117, 0xffff0000, v184
	v_pk_add_f32 v[112:113], v[112:113], v[116:117]
	v_lshlrev_b32_e32 v116, 16, v185
	v_and_b32_e32 v117, 0xffff0000, v185
	v_pk_add_f32 v[114:115], v[114:115], v[116:117]
	v_cvt_pk_bf16_f32 v112, v112, v113
	v_cvt_pk_bf16_f32 v113, v114, v115
	v_lshlrev_b32_e32 v114, 16, v186
	v_and_b32_e32 v115, 0xffff0000, v186
	v_pk_add_f32 v[108:109], v[108:109], v[114:115]
	v_lshl_add_u64 v[124:125], v[124:125], 0, v[202:203]
	v_cvt_pk_bf16_f32 v114, v108, v109
	v_lshlrev_b32_e32 v108, 16, v187
	v_and_b32_e32 v109, 0xffff0000, v187
	v_pk_add_f32 v[108:109], v[110:111], v[108:109]
	s_waitcnt vmcnt(12)
	v_lshlrev_b32_e32 v110, 16, v180
	v_and_b32_e32 v111, 0xffff0000, v180
	v_pk_add_f32 v[104:105], v[104:105], v[110:111]
	v_lshlrev_b32_e32 v110, 16, v181
	v_and_b32_e32 v111, 0xffff0000, v181
	v_pk_add_f32 v[106:107], v[106:107], v[110:111]
	v_cvt_pk_bf16_f32 v104, v104, v105
	v_cvt_pk_bf16_f32 v105, v106, v107
	v_lshlrev_b32_e32 v106, 16, v182
	v_and_b32_e32 v107, 0xffff0000, v182
	v_pk_add_f32 v[96:97], v[96:97], v[106:107]
	v_cvt_pk_bf16_f32 v115, v108, v109
	v_cvt_pk_bf16_f32 v106, v96, v97
	v_lshlrev_b32_e32 v96, 16, v183
	v_and_b32_e32 v97, 0xffff0000, v183
	v_pk_add_f32 v[96:97], v[98:99], v[96:97]
	s_waitcnt vmcnt(11)
	v_lshlrev_b32_e32 v98, 16, v177
	v_cvt_pk_bf16_f32 v107, v96, v97
	v_lshlrev_b32_e32 v96, 16, v176
	v_and_b32_e32 v97, 0xffff0000, v176
	v_and_b32_e32 v99, 0xffff0000, v177
	v_pk_add_f32 v[96:97], v[100:101], v[96:97]
	v_pk_add_f32 v[98:99], v[102:103], v[98:99]
	v_cvt_pk_bf16_f32 v96, v96, v97
	v_cvt_pk_bf16_f32 v97, v98, v99
	v_lshlrev_b32_e32 v98, 16, v178
	v_and_b32_e32 v99, 0xffff0000, v178
	v_pk_add_f32 v[92:93], v[92:93], v[98:99]
	v_lshl_add_u64 v[108:109], s[88:89], 0, v[222:223]
	v_cvt_pk_bf16_f32 v98, v92, v93
	v_lshlrev_b32_e32 v92, 16, v179
	v_and_b32_e32 v93, 0xffff0000, v179
	v_pk_add_f32 v[92:93], v[94:95], v[92:93]
	s_waitcnt vmcnt(10)
	v_lshlrev_b32_e32 v94, 16, v168
	v_and_b32_e32 v95, 0xffff0000, v168
	v_pk_add_f32 v[88:89], v[88:89], v[94:95]
	v_lshlrev_b32_e32 v94, 16, v169
	v_and_b32_e32 v95, 0xffff0000, v169
	v_pk_add_f32 v[90:91], v[90:91], v[94:95]
	v_cvt_pk_bf16_f32 v88, v88, v89
	v_cvt_pk_bf16_f32 v89, v90, v91
	v_lshlrev_b32_e32 v90, 16, v170
	v_and_b32_e32 v91, 0xffff0000, v170
	v_pk_add_f32 v[80:81], v[80:81], v[90:91]
	v_cvt_pk_bf16_f32 v99, v92, v93
	v_cvt_pk_bf16_f32 v90, v80, v81
	v_lshlrev_b32_e32 v80, 16, v171
	v_and_b32_e32 v81, 0xffff0000, v171
	v_pk_add_f32 v[80:81], v[82:83], v[80:81]
	s_waitcnt vmcnt(9)
	v_lshlrev_b32_e32 v82, 16, v173
	v_cvt_pk_bf16_f32 v91, v80, v81
	v_lshlrev_b32_e32 v80, 16, v172
	v_and_b32_e32 v81, 0xffff0000, v172
	v_and_b32_e32 v83, 0xffff0000, v173
	v_pk_add_f32 v[80:81], v[84:85], v[80:81]
	v_pk_add_f32 v[82:83], v[86:87], v[82:83]
	v_cvt_pk_bf16_f32 v80, v80, v81
	v_cvt_pk_bf16_f32 v81, v82, v83
	v_lshlrev_b32_e32 v82, 16, v174
	v_and_b32_e32 v83, 0xffff0000, v174
	v_pk_add_f32 v[76:77], v[76:77], v[82:83]
	v_lshl_add_u64 v[92:93], s[88:89], 0, v[220:221]
	v_cvt_pk_bf16_f32 v82, v76, v77
	v_lshlrev_b32_e32 v76, 16, v175
	v_and_b32_e32 v77, 0xffff0000, v175
	v_pk_add_f32 v[76:77], v[78:79], v[76:77]
	s_waitcnt vmcnt(8)
	v_lshlrev_b32_e32 v78, 16, v164
	v_and_b32_e32 v79, 0xffff0000, v164
	v_pk_add_f32 v[72:73], v[72:73], v[78:79]
	v_lshlrev_b32_e32 v78, 16, v165
	v_and_b32_e32 v79, 0xffff0000, v165
	v_pk_add_f32 v[74:75], v[74:75], v[78:79]
	v_cvt_pk_bf16_f32 v72, v72, v73
	v_cvt_pk_bf16_f32 v73, v74, v75
	v_lshlrev_b32_e32 v74, 16, v166
	v_and_b32_e32 v75, 0xffff0000, v166
	v_pk_add_f32 v[68:69], v[68:69], v[74:75]
	v_cvt_pk_bf16_f32 v83, v76, v77
	v_cvt_pk_bf16_f32 v74, v68, v69
	v_lshlrev_b32_e32 v68, 16, v167
	v_and_b32_e32 v69, 0xffff0000, v167
	v_pk_add_f32 v[68:69], v[70:71], v[68:69]
	v_lshl_add_u64 v[76:77], s[88:89], 0, v[212:213]
	v_cvt_pk_bf16_f32 v75, v68, v69
	s_waitcnt vmcnt(7)
	v_lshlrev_b32_e32 v68, 16, v160
	v_and_b32_e32 v69, 0xffff0000, v160
	v_pk_add_f32 v[64:65], v[64:65], v[68:69]
	v_lshlrev_b32_e32 v68, 16, v161
	v_and_b32_e32 v69, 0xffff0000, v161
	v_pk_add_f32 v[66:67], v[66:67], v[68:69]
	v_cvt_pk_bf16_f32 v64, v64, v65
	v_cvt_pk_bf16_f32 v65, v66, v67
	v_lshlrev_b32_e32 v66, 16, v162
	v_and_b32_e32 v67, 0xffff0000, v162
	v_pk_add_f32 v[60:61], v[60:61], v[66:67]
	v_lshl_add_u64 v[108:109], v[108:109], 0, v[202:203]
	v_cvt_pk_bf16_f32 v66, v60, v61
	v_lshlrev_b32_e32 v60, 16, v163
	v_and_b32_e32 v61, 0xffff0000, v163
	v_pk_add_f32 v[60:61], v[62:63], v[60:61]
	s_waitcnt vmcnt(6)
; __device__ __forceinline__ unsigned cvt_pk_bf16(float lo, float hi) { const f32x2 v = {lo, hi}; const bf16v2_ r = __builtin_convertvector(v, bf16v2_); return __builtin_bit_cast(unsigned, r); }
; __device__ __forceinline__ float bflo(unsigned w) { return __uint_as_float(w << 16); }
; __device__ __forceinline__ float bfhi(unsigned w) { return __uint_as_float(w & 0xffff0000u); }
; #define PG8_WAIT_V(n) asm volatile("s_waitcnt vmcnt(" #n ")" ::: "memory")
; #define PG8_BAR __builtin_amdgcn_s_barrier()
;     __device__ __forceinline__ void operator()(const f32x4 (&acc)[2][2][4][2], const Unit& u, int wr, int wc, int, int) const {
;     ...
;                 for (int bj = 0; bj < 2; ++bj) { const u32x4 c = cin[ai][m][bj]; const f32x4 v0 = acc[ai][bj][m][0], v1 = acc[ai][bj][m][1];
;                     u32x4 w; w.x = cvt_pk_bf16(bflo(c.x) + v0[0], bfhi(c.x) + v0[1]); w.y = cvt_pk_bf16(bflo(c.y) + v0[2], bfhi(c.y) + v0[3]);
;                     w.z = cvt_pk_bf16(bflo(c.z) + v1[0], bfhi(c.z) + v1[1]); w.w = cvt_pk_bf16(bflo(c.w) + v1[2], bfhi(c.w) + v1[3]);
;                     *(u32x4*)(C + (size_t)(row0 + ai * HALF + m * 16) * ldc + col0 + bj * HALF) = w; }
; template <class Epi, class Sched>
; __device__ __forceinline__ void gemm_phase(LAS unsigned char* lds, const Gemm g, const Sched& S, const Epi& E) {
;     ...
;     PG8_WAIT_V(0);
;     if (wr == 0) PG8_BAR;
;     PG8_BAR;
	v_lshlrev_b32_e32 v62, 16, v156
	v_and_b32_e32 v63, 0xffff0000, v156
	v_pk_add_f32 v[56:57], v[56:57], v[62:63]
	v_lshlrev_b32_e32 v62, 16, v157
	v_and_b32_e32 v63, 0xffff0000, v157
	v_pk_add_f32 v[58:59], v[58:59], v[62:63]
	v_cvt_pk_bf16_f32 v56, v56, v57
	v_cvt_pk_bf16_f32 v57, v58, v59
	v_lshlrev_b32_e32 v58, 16, v158
	v_and_b32_e32 v59, 0xffff0000, v158
	v_pk_add_f32 v[48:49], v[48:49], v[58:59]
	v_cvt_pk_bf16_f32 v67, v60, v61
	v_cvt_pk_bf16_f32 v58, v48, v49
	v_lshlrev_b32_e32 v48, 16, v159
	v_and_b32_e32 v49, 0xffff0000, v159
	v_pk_add_f32 v[48:49], v[50:51], v[48:49]
	s_waitcnt vmcnt(5)
	v_lshlrev_b32_e32 v50, 16, v153
	v_cvt_pk_bf16_f32 v59, v48, v49
	v_lshlrev_b32_e32 v48, 16, v152
	v_and_b32_e32 v49, 0xffff0000, v152
	v_and_b32_e32 v51, 0xffff0000, v153
	v_pk_add_f32 v[48:49], v[52:53], v[48:49]
	v_pk_add_f32 v[50:51], v[54:55], v[50:51]
	v_cvt_pk_bf16_f32 v48, v48, v49
	v_cvt_pk_bf16_f32 v49, v50, v51
	v_lshlrev_b32_e32 v50, 16, v154
	v_and_b32_e32 v51, 0xffff0000, v154
	v_pk_add_f32 v[44:45], v[44:45], v[50:51]
	v_lshl_add_u64 v[60:61], s[88:89], 0, v[210:211]
	v_cvt_pk_bf16_f32 v50, v44, v45
	v_lshlrev_b32_e32 v44, 16, v155
	v_and_b32_e32 v45, 0xffff0000, v155
	v_pk_add_f32 v[44:45], v[46:47], v[44:45]
	s_waitcnt vmcnt(4)
	v_lshlrev_b32_e32 v46, 16, v148
	v_and_b32_e32 v47, 0xffff0000, v148
	v_pk_add_f32 v[40:41], v[40:41], v[46:47]
	v_lshlrev_b32_e32 v46, 16, v149
	v_and_b32_e32 v47, 0xffff0000, v149
	v_pk_add_f32 v[42:43], v[42:43], v[46:47]
	v_cvt_pk_bf16_f32 v40, v40, v41
	v_cvt_pk_bf16_f32 v41, v42, v43
	v_lshlrev_b32_e32 v42, 16, v150
	v_and_b32_e32 v43, 0xffff0000, v150
	v_pk_add_f32 v[32:33], v[32:33], v[42:43]
	v_cvt_pk_bf16_f32 v51, v44, v45
	v_cvt_pk_bf16_f32 v42, v32, v33
	v_lshlrev_b32_e32 v32, 16, v151
	v_and_b32_e32 v33, 0xffff0000, v151
	v_pk_add_f32 v[32:33], v[34:35], v[32:33]
	s_waitcnt vmcnt(3)
	v_lshlrev_b32_e32 v34, 16, v145
	v_cvt_pk_bf16_f32 v43, v32, v33
	v_lshlrev_b32_e32 v32, 16, v144
	v_and_b32_e32 v33, 0xffff0000, v144
	v_and_b32_e32 v35, 0xffff0000, v145
	v_pk_add_f32 v[32:33], v[36:37], v[32:33]
	v_pk_add_f32 v[34:35], v[38:39], v[34:35]
	v_cvt_pk_bf16_f32 v32, v32, v33
	v_cvt_pk_bf16_f32 v33, v34, v35
	v_lshlrev_b32_e32 v34, 16, v146
	v_and_b32_e32 v35, 0xffff0000, v146
	v_pk_add_f32 v[28:29], v[28:29], v[34:35]
	v_lshl_add_u64 v[44:45], s[88:89], 0, v[208:209]
	v_cvt_pk_bf16_f32 v34, v28, v29
	v_lshlrev_b32_e32 v28, 16, v147
	v_and_b32_e32 v29, 0xffff0000, v147
	v_pk_add_f32 v[28:29], v[30:31], v[28:29]
	s_waitcnt vmcnt(2)
	v_lshlrev_b32_e32 v30, 16, v140
	v_and_b32_e32 v31, 0xffff0000, v140
	v_pk_add_f32 v[24:25], v[24:25], v[30:31]
	v_lshlrev_b32_e32 v30, 16, v141
	v_and_b32_e32 v31, 0xffff0000, v141
	v_pk_add_f32 v[26:27], v[26:27], v[30:31]
	v_cvt_pk_bf16_f32 v24, v24, v25
	v_cvt_pk_bf16_f32 v25, v26, v27
	v_lshlrev_b32_e32 v26, 16, v142
	v_and_b32_e32 v27, 0xffff0000, v142
	v_pk_add_f32 v[16:17], v[16:17], v[26:27]
	v_cvt_pk_bf16_f32 v35, v28, v29
	v_cvt_pk_bf16_f32 v26, v16, v17
	v_lshlrev_b32_e32 v16, 16, v143
	v_and_b32_e32 v17, 0xffff0000, v143
	v_pk_add_f32 v[16:17], v[18:19], v[16:17]
	s_waitcnt vmcnt(1)
	v_lshlrev_b32_e32 v18, 16, v137
	v_cvt_pk_bf16_f32 v27, v16, v17
	v_lshlrev_b32_e32 v16, 16, v136
	v_and_b32_e32 v17, 0xffff0000, v136
	v_and_b32_e32 v19, 0xffff0000, v137
	v_pk_add_f32 v[16:17], v[20:21], v[16:17]
	v_pk_add_f32 v[18:19], v[22:23], v[18:19]
	v_cvt_pk_bf16_f32 v16, v16, v17
	v_cvt_pk_bf16_f32 v17, v18, v19
	v_lshlrev_b32_e32 v18, 16, v138
	v_and_b32_e32 v19, 0xffff0000, v138
	v_pk_add_f32 v[12:13], v[12:13], v[18:19]
	v_lshl_add_u64 v[28:29], s[88:89], 0, v[206:207]
	v_cvt_pk_bf16_f32 v18, v12, v13
	v_lshlrev_b32_e32 v12, 16, v139
	v_and_b32_e32 v13, 0xffff0000, v139
	v_pk_add_f32 v[12:13], v[14:15], v[12:13]
	s_waitcnt vmcnt(0)
	v_lshlrev_b32_e32 v14, 16, v132
	v_and_b32_e32 v15, 0xffff0000, v132
	v_pk_add_f32 v[8:9], v[8:9], v[14:15]
	v_lshlrev_b32_e32 v14, 16, v133
	v_and_b32_e32 v15, 0xffff0000, v133
	v_pk_add_f32 v[10:11], v[10:11], v[14:15]
	v_cvt_pk_bf16_f32 v8, v8, v9
	v_cvt_pk_bf16_f32 v9, v10, v11
	v_lshlrev_b32_e32 v10, 16, v134
	v_and_b32_e32 v11, 0xffff0000, v134
	v_pk_add_f32 v[4:5], v[4:5], v[10:11]
	v_cvt_pk_bf16_f32 v19, v12, v13
	v_cvt_pk_bf16_f32 v10, v4, v5
	v_lshlrev_b32_e32 v4, 16, v135
	v_and_b32_e32 v5, 0xffff0000, v135
	v_lshl_add_u64 v[12:13], s[88:89], 0, v[204:205]
	v_pk_add_f32 v[4:5], v[6:7], v[4:5]
	v_lshl_add_u64 v[92:93], v[92:93], 0, v[202:203]
	v_lshl_add_u64 v[76:77], v[76:77], 0, v[202:203]
	v_lshl_add_u64 v[60:61], v[60:61], 0, v[202:203]
	v_lshl_add_u64 v[44:45], v[44:45], 0, v[202:203]
	v_lshl_add_u64 v[28:29], v[28:29], 0, v[202:203]
	v_lshl_add_u64 v[12:13], v[12:13], 0, v[202:203]
	v_cvt_pk_bf16_f32 v11, v4, v5
	global_store_dwordx4 v[124:125], v[128:131], off
	global_store_dwordx4 v[124:125], v[120:123], off offset:256
	global_store_dwordx4 v[108:109], v[112:115], off
	global_store_dwordx4 v[108:109], v[104:107], off offset:256
	global_store_dwordx4 v[92:93], v[96:99], off
	global_store_dwordx4 v[92:93], v[88:91], off offset:256
	global_store_dwordx4 v[76:77], v[80:83], off
	global_store_dwordx4 v[76:77], v[72:75], off offset:256
	global_store_dwordx4 v[60:61], v[64:67], off
	global_store_dwordx4 v[60:61], v[56:59], off offset:256
	global_store_dwordx4 v[44:45], v[48:51], off
	global_store_dwordx4 v[44:45], v[40:43], off offset:256
	global_store_dwordx4 v[28:29], v[32:35], off
	global_store_dwordx4 v[28:29], v[24:27], off offset:256
	global_store_dwordx4 v[12:13], v[16:19], off
	global_store_dwordx4 v[12:13], v[8:11], off offset:256
	s_cbranch_vccz .LBB0_959
	s_waitcnt vmcnt(0)
	s_cmpk_gt_u32 s2, 0xff
	s_cbranch_scc1 .LBB0_970
	s_barrier

; #define PG8_STAGE(bufoff, gbase, voff) do { _Pragma("unroll") for (int _i = 0; _i < 2; ++_i) \
;         __builtin_amdgcn_global_load_lds((const unsigned*)((const char*)(gbase) + (voff)[_i]), (LAS unsigned*)(lds + (bufoff) + ldsw + _i * 8192), 16, 0, 0); } while (0)
; #define PG8_LDA(dst, b, h) do { _Pragma("unroll") for (int m = 0; m < 4; ++m) _Pragma("unroll") for (int k = 0; k < 2; ++k) dst[m][k] = *(const LAS bf16x8*)(lds + PG8_SA(b, h) + aoff + m * 2048 + k * 1024); } while (0)
; #define PG8_LDB(dst, b, h) do { _Pragma("unroll") for (int n = 0; n < 2; ++n) _Pragma("unroll") for (int k = 0; k < 2; ++k) dst[n][k] = *(const LAS bf16x8*)(lds + PG8_SB(b, h) + boff + n * 2048 + k * 1024); } while (0)
; #define PG8_MMA(ai, bj, At, Bt) do { __builtin_amdgcn_s_setprio(1); _Pragma("unroll") for (int m = 0; m < 4; ++m) _Pragma("unroll") for (int n = 0; n < 2; ++n) _Pragma("unroll") for (int k = 0; k < 2; ++k) \
;         acc[ai][bj][m][n] = __builtin_amdgcn_mfma_f32_16x16x32_bf16(Bt[n][k], At[m][k], acc[ai][bj][m][n], 0, 0, 0); __builtin_amdgcn_s_setprio(0); } while (0)
; #define PG8_WAIT_V(n) asm volatile("s_waitcnt vmcnt(" #n ")" ::: "memory")
; #define PG8_BAR __builtin_amdgcn_s_barrier()
; template <class Epi, class Sched>
; __device__ __forceinline__ void gemm_phase(LAS unsigned char* lds, const Gemm g, const Sched& S, const Epi& E) {
;     ...
;         for (int t = 0; t < nt; t += 2) {
;             const bool last = (t == nt - 2);
;             const char* a1 = cA + (size_t)(t + 1) * kstep;
;             const char* a2 = last ? nA : cA + (size_t)(t + 2) * kstep; const char* b2 = last ? nB : cB + (size_t)(t + 2) * kstep;
;             const char* a3 = a2 + kstep; const char* b3 = b2 + kstep;
;             if (last && has_next) S.a_ready(nxt);
;             PG8_LDB(B0, 0, 0); PG8_SCHED; PG8_LDA(At, 0, 0); PG8_STAGE(PG8_SA(1, 1), a1 + hstepA, voffA);
;             PG8_WAIT_L(8); PG8_BAR; PG8_WAIT_L(0); PG8_MMA(0, 0, At, B0); PG8_BAR; PG8_SCHED;
;             PG8_LDB(B1, 0, 1); PG8_STAGE(PG8_SB(0, 0), b2, voffB);
;             PG8_BAR; PG8_WAIT_L(0); PG8_MMA(0, 1, At, B1); PG8_BAR;
;             PG8_LDA(At, 0, 1); PG8_STAGE(PG8_SA(0, 0), a2, voffA);
;             PG8_BAR; PG8_WAIT_L(0); PG8_MMA(1, 0, At, B0); PG8_BAR; PG8_SCHED;
;             PG8_STAGE(PG8_SB(0, 1), b2 + hstepB, voffB);
;             PG8_WAIT_V(6); PG8_BAR; PG8_MMA(1, 1, At, B1); PG8_BAR;
.LBB0_1396:
	s_setprio 0
	s_add_u32 s20, s6, 0xfff80080
	s_addc_u32 s21, s7, -1
	s_add_i32 s52, 0, 0x10000
	v_add_u32_e32 v144, s52, v1
	ds_read_b128 v[132:135], v144
	ds_read_b128 v[136:139], v144 offset:1024
	ds_read_b128 v[140:143], v144 offset:2048
	ds_read_b128 v[144:147], v144 offset:3072
	s_cmp_eq_u32 s51, 28
	s_cselect_b32 s25, s15, s21
	s_cselect_b32 s24, s47, s20
	s_cselect_b32 s21, s1, s50
	s_cselect_b32 s20, s48, s49
	ds_read_b128 v[148:151], v224
	ds_read_b128 v[152:155], v224 offset:1024
	ds_read_b128 v[156:159], v224 offset:2048
	ds_read_b128 v[160:163], v224 offset:3072
	ds_read_b128 v[164:167], v224 offset:4096
	ds_read_b128 v[168:171], v224 offset:5120
	ds_read_b128 v[172:175], v224 offset:6144
	ds_read_b128 v[176:179], v224 offset:7168
	s_add_i32 s54, 0, 0x14000
	v_add_u32_e32 v202, s54, v1
	ds_read_b128 v[180:183], v202
	ds_read_b128 v[184:187], v202 offset:1024
	ds_read_b128 v[188:191], v202 offset:2048
	ds_read_b128 v[202:205], v202 offset:3072
	s_add_i32 m0, s31, 0xc000
	s_nop 0
	global_load_lds_dwordx4 v198, s[6:7]
	s_add_i32 m0, s31, 0xe000
	s_nop 0
	global_load_lds_dwordx4 v200, s[6:7]
	s_waitcnt lgkmcnt(0)
	s_setprio 1
	s_barrier
	v_mfma_f32_16x16x32_bf16 v[128:131], v[132:135], v[148:151], v[128:131]
	v_mfma_f32_16x16x32_bf16 v[124:127], v[140:143], v[148:151], v[124:127]
	v_mfma_f32_16x16x32_bf16 v[112:115], v[132:135], v[156:159], v[112:115]
	v_mfma_f32_16x16x32_bf16 v[108:111], v[140:143], v[156:159], v[108:111]
	v_mfma_f32_16x16x32_bf16 v[100:103], v[132:135], v[164:167], v[100:103]
	v_mfma_f32_16x16x32_bf16 v[92:95], v[140:143], v[164:167], v[92:95]
	v_mfma_f32_16x16x32_bf16 v[84:87], v[132:135], v[172:175], v[84:87]
	v_mfma_f32_16x16x32_bf16 v[76:79], v[140:143], v[172:175], v[76:79]
	v_mfma_f32_16x16x32_bf16 v[128:131], v[136:139], v[152:155], v[128:131]
	v_mfma_f32_16x16x32_bf16 v[124:127], v[144:147], v[152:155], v[124:127]
	v_mfma_f32_16x16x32_bf16 v[112:115], v[136:139], v[160:163], v[112:115]
	v_mfma_f32_16x16x32_bf16 v[108:111], v[144:147], v[160:163], v[108:111]
	v_mfma_f32_16x16x32_bf16 v[100:103], v[136:139], v[168:171], v[100:103]
	v_mfma_f32_16x16x32_bf16 v[92:95], v[144:147], v[168:171], v[92:95]
	v_mfma_f32_16x16x32_bf16 v[84:87], v[136:139], v[176:179], v[84:87]
	v_mfma_f32_16x16x32_bf16 v[76:79], v[144:147], v[176:179], v[76:79]
	v_mfma_f32_16x16x32_bf16 v[120:123], v[180:183], v[148:151], v[120:123]
	v_mfma_f32_16x16x32_bf16 v[116:119], v[188:191], v[148:151], v[116:119]
	v_mfma_f32_16x16x32_bf16 v[104:107], v[180:183], v[156:159], v[104:107]
	v_mfma_f32_16x16x32_bf16 v[96:99], v[188:191], v[156:159], v[96:99]
	v_mfma_f32_16x16x32_bf16 v[88:91], v[180:183], v[164:167], v[88:91]
	v_mfma_f32_16x16x32_bf16 v[80:83], v[188:191], v[164:167], v[80:83]
	v_mfma_f32_16x16x32_bf16 v[72:75], v[180:183], v[172:175], v[72:75]
	v_mfma_f32_16x16x32_bf16 v[68:71], v[188:191], v[172:175], v[68:71]
	v_mfma_f32_16x16x32_bf16 v[120:123], v[184:187], v[152:155], v[120:123]
	v_mfma_f32_16x16x32_bf16 v[116:119], v[202:205], v[152:155], v[116:119]
	v_mfma_f32_16x16x32_bf16 v[104:107], v[184:187], v[160:163], v[104:107]
	v_mfma_f32_16x16x32_bf16 v[96:99], v[202:205], v[160:163], v[96:99]
	v_mfma_f32_16x16x32_bf16 v[88:91], v[184:187], v[168:171], v[88:91]
	v_mfma_f32_16x16x32_bf16 v[80:83], v[202:205], v[168:171], v[80:83]
	v_mfma_f32_16x16x32_bf16 v[72:75], v[184:187], v[176:179], v[72:75]
	v_mfma_f32_16x16x32_bf16 v[68:71], v[202:205], v[176:179], v[68:71]
	s_barrier
	s_setprio 0
	ds_read_b128 v[148:151], v224 offset:16384
	ds_read_b128 v[152:155], v224 offset:17408
	ds_read_b128 v[156:159], v224 offset:18432
	ds_read_b128 v[160:163], v224 offset:19456
	ds_read_b128 v[164:167], v224 offset:20480
	ds_read_b128 v[168:171], v224 offset:21504
	ds_read_b128 v[172:175], v224 offset:22528
	ds_read_b128 v[176:179], v224 offset:23552
	s_add_i32 s52, s52, s30
	v_lshl_add_u64 v[206:207], s[20:21], 0, v[2:3]
	s_mov_b32 m0, s52
	s_nop 0
	global_load_lds_dwordx4 v[206:207], off
	v_lshl_add_u64 v[208:209], s[20:21], 0, v[192:193]
	s_add_i32 m0, s52, 0x2000
	s_nop 0
	global_load_lds_dwordx4 v[208:209], off
	s_mov_b32 m0, s31
	v_lshl_add_u64 v[210:211], s[24:25], 0, v[196:197]
	global_load_lds_dwordx4 v[210:211], off
	v_lshl_add_u64 v[212:213], s[24:25], 0, v[194:195]
	s_mov_b32 m0, s35
	s_nop 0
	global_load_lds_dwordx4 v[212:213], off
	s_add_u32 s52, s20, 0x80000
	s_addc_u32 s53, s21, 0
	s_add_i32 s54, s54, s30
	s_mov_b32 m0, s54
	s_nop 0
	global_load_lds_dwordx4 v2, s[52:53]
	s_add_i32 m0, s54, 0x2000
	s_nop 0
	global_load_lds_dwordx4 v192, s[52:53]
	s_waitcnt lgkmcnt(0)
	s_waitcnt vmcnt(6)
	s_setprio 1
	s_barrier
; #define PG8_STAGE(bufoff, gbase, voff) do { _Pragma("unroll") for (int _i = 0; _i < 2; ++_i) \
;         __builtin_amdgcn_global_load_lds((const unsigned*)((const char*)(gbase) + (voff)[_i]), (LAS unsigned*)(lds + (bufoff) + ldsw + _i * 8192), 16, 0, 0); } while (0)
; #define PG8_LDA(dst, b, h) do { _Pragma("unroll") for (int m = 0; m < 4; ++m) _Pragma("unroll") for (int k = 0; k < 2; ++k) dst[m][k] = *(const LAS bf16x8*)(lds + PG8_SA(b, h) + aoff + m * 2048 + k * 1024); } while (0)
; #define PG8_LDB(dst, b, h) do { _Pragma("unroll") for (int n = 0; n < 2; ++n) _Pragma("unroll") for (int k = 0; k < 2; ++k) dst[n][k] = *(const LAS bf16x8*)(lds + PG8_SB(b, h) + boff + n * 2048 + k * 1024); } while (0)
; #define PG8_MMA(ai, bj, At, Bt) do { __builtin_amdgcn_s_setprio(1); _Pragma("unroll") for (int m = 0; m < 4; ++m) _Pragma("unroll") for (int n = 0; n < 2; ++n) _Pragma("unroll") for (int k = 0; k < 2; ++k) \
;         acc[ai][bj][m][n] = __builtin_amdgcn_mfma_f32_16x16x32_bf16(Bt[n][k], At[m][k], acc[ai][bj][m][n], 0, 0, 0); __builtin_amdgcn_s_setprio(0); } while (0)
; #define PG8_WAIT_V(n) asm volatile("s_waitcnt vmcnt(" #n ")" ::: "memory")
; #define PG8_WAIT_L(n) asm volatile("s_waitcnt lgkmcnt(" #n ")" ::: "memory")
; #define PG8_BAR __builtin_amdgcn_s_barrier()
; #define PG8_SCHED __builtin_amdgcn_sched_barrier(0)
; template <class Epi, class Sched>
; __device__ __forceinline__ void gemm_phase(LAS unsigned char* lds, const Gemm g, const Sched& S, const Epi& E) {
;     ...
;             PG8_WAIT_V(6); PG8_BAR; PG8_MMA(1, 1, At, B1); PG8_BAR;
;             PG8_LDB(B0, 1, 0); PG8_SCHED; PG8_LDA(At, 1, 0); PG8_STAGE(PG8_SA(0, 1), a2 + hstepA, voffA);
;             PG8_WAIT_L(8); PG8_BAR; PG8_WAIT_L(0); PG8_MMA(0, 0, At, B0); PG8_BAR; PG8_SCHED;
;             PG8_LDB(B1, 1, 1); PG8_STAGE(PG8_SB(1, 0), b3, voffB);
;             PG8_BAR; PG8_WAIT_L(0); PG8_MMA(0, 1, At, B1); PG8_BAR;
;             PG8_LDA(At, 1, 1); PG8_STAGE(PG8_SA(1, 0), a3, voffA);
;             PG8_BAR; PG8_WAIT_L(0); PG8_MMA(1, 0, At, B0); PG8_BAR; PG8_SCHED;
	v_mfma_f32_16x16x32_bf16 v[64:67], v[132:135], v[148:151], v[64:67]
	v_mfma_f32_16x16x32_bf16 v[60:63], v[140:143], v[148:151], v[60:63]
	v_mfma_f32_16x16x32_bf16 v[52:55], v[132:135], v[156:159], v[52:55]
	v_mfma_f32_16x16x32_bf16 v[44:47], v[140:143], v[156:159], v[44:47]
	v_mfma_f32_16x16x32_bf16 v[36:39], v[132:135], v[164:167], v[36:39]
	v_mfma_f32_16x16x32_bf16 v[28:31], v[140:143], v[164:167], v[28:31]
	v_mfma_f32_16x16x32_bf16 v[20:23], v[132:135], v[172:175], v[20:23]
	v_mfma_f32_16x16x32_bf16 v[12:15], v[140:143], v[172:175], v[12:15]
	v_mfma_f32_16x16x32_bf16 v[64:67], v[136:139], v[152:155], v[64:67]
	v_mfma_f32_16x16x32_bf16 v[60:63], v[144:147], v[152:155], v[60:63]
	v_mfma_f32_16x16x32_bf16 v[52:55], v[136:139], v[160:163], v[52:55]
	v_mfma_f32_16x16x32_bf16 v[44:47], v[144:147], v[160:163], v[44:47]
	v_mfma_f32_16x16x32_bf16 v[36:39], v[136:139], v[168:171], v[36:39]
	v_mfma_f32_16x16x32_bf16 v[28:31], v[144:147], v[168:171], v[28:31]
	v_mfma_f32_16x16x32_bf16 v[20:23], v[136:139], v[176:179], v[20:23]
	v_mfma_f32_16x16x32_bf16 v[12:15], v[144:147], v[176:179], v[12:15]
	v_mfma_f32_16x16x32_bf16 v[56:59], v[180:183], v[148:151], v[56:59]
	v_mfma_f32_16x16x32_bf16 v[48:51], v[188:191], v[148:151], v[48:51]
	v_mfma_f32_16x16x32_bf16 v[40:43], v[180:183], v[156:159], v[40:43]
	v_mfma_f32_16x16x32_bf16 v[32:35], v[188:191], v[156:159], v[32:35]
	v_mfma_f32_16x16x32_bf16 v[24:27], v[180:183], v[164:167], v[24:27]
	v_mfma_f32_16x16x32_bf16 v[16:19], v[188:191], v[164:167], v[16:19]
	v_mfma_f32_16x16x32_bf16 v[8:11], v[180:183], v[172:175], v[8:11]
	v_mfma_f32_16x16x32_bf16 v[4:7], v[188:191], v[172:175], v[4:7]
	v_mfma_f32_16x16x32_bf16 v[56:59], v[184:187], v[152:155], v[56:59]
	v_mfma_f32_16x16x32_bf16 v[48:51], v[202:205], v[152:155], v[48:51]
	v_mfma_f32_16x16x32_bf16 v[40:43], v[184:187], v[160:163], v[40:43]
	v_mfma_f32_16x16x32_bf16 v[32:35], v[202:205], v[160:163], v[32:35]
	v_mfma_f32_16x16x32_bf16 v[24:27], v[184:187], v[168:171], v[24:27]
	v_mfma_f32_16x16x32_bf16 v[16:19], v[202:205], v[168:171], v[16:19]
	v_mfma_f32_16x16x32_bf16 v[8:11], v[184:187], v[176:179], v[8:11]
	v_mfma_f32_16x16x32_bf16 v[4:7], v[202:205], v[176:179], v[4:7]
	s_barrier
	s_setprio 0
	s_add_i32 s52, 0, 0x18000
	v_add_u32_e32 v144, s52, v1
	ds_read_b128 v[132:135], v144
	ds_read_b128 v[136:139], v144 offset:1024
	ds_read_b128 v[140:143], v144 offset:2048
	ds_read_b128 v[144:147], v144 offset:3072
	s_add_u32 s24, s24, 0x80000
	s_addc_u32 s25, s25, 0
	ds_read_b128 v[148:151], v224 offset:32768
	ds_read_b128 v[152:155], v224 offset:33792
	ds_read_b128 v[156:159], v224 offset:34816
	ds_read_b128 v[160:163], v224 offset:35840
	ds_read_b128 v[164:167], v224 offset:36864
	ds_read_b128 v[168:171], v224 offset:37888
	ds_read_b128 v[172:175], v224 offset:38912
	ds_read_b128 v[176:179], v224 offset:39936
	s_mov_b32 m0, s36
	s_nop 0
	global_load_lds_dwordx4 v196, s[24:25]
	s_mov_b32 m0, s37
	s_nop 0
	global_load_lds_dwordx4 v194, s[24:25]
	s_add_i32 s24, 0, 0x1c000
	v_add_u32_e32 v202, s24, v1
	ds_read_b128 v[180:183], v202
	ds_read_b128 v[184:187], v202 offset:1024
	ds_read_b128 v[188:191], v202 offset:2048
	ds_read_b128 v[202:205], v202 offset:3072
	s_waitcnt lgkmcnt(0)
	s_setprio 1
	s_barrier
	v_mfma_f32_16x16x32_bf16 v[128:131], v[132:135], v[148:151], v[128:131]
	v_mfma_f32_16x16x32_bf16 v[124:127], v[140:143], v[148:151], v[124:127]
	v_mfma_f32_16x16x32_bf16 v[112:115], v[132:135], v[156:159], v[112:115]
	v_mfma_f32_16x16x32_bf16 v[108:111], v[140:143], v[156:159], v[108:111]
	v_mfma_f32_16x16x32_bf16 v[100:103], v[132:135], v[164:167], v[100:103]
	v_mfma_f32_16x16x32_bf16 v[92:95], v[140:143], v[164:167], v[92:95]
	v_mfma_f32_16x16x32_bf16 v[84:87], v[132:135], v[172:175], v[84:87]
	v_mfma_f32_16x16x32_bf16 v[76:79], v[140:143], v[172:175], v[76:79]
	v_mfma_f32_16x16x32_bf16 v[128:131], v[136:139], v[152:155], v[128:131]
	v_mfma_f32_16x16x32_bf16 v[124:127], v[144:147], v[152:155], v[124:127]
	v_mfma_f32_16x16x32_bf16 v[112:115], v[136:139], v[160:163], v[112:115]
	v_mfma_f32_16x16x32_bf16 v[108:111], v[144:147], v[160:163], v[108:111]
	v_mfma_f32_16x16x32_bf16 v[100:103], v[136:139], v[168:171], v[100:103]
	v_mfma_f32_16x16x32_bf16 v[92:95], v[144:147], v[168:171], v[92:95]
	v_mfma_f32_16x16x32_bf16 v[84:87], v[136:139], v[176:179], v[84:87]
	v_mfma_f32_16x16x32_bf16 v[76:79], v[144:147], v[176:179], v[76:79]
	v_mfma_f32_16x16x32_bf16 v[120:123], v[180:183], v[148:151], v[120:123]
	v_mfma_f32_16x16x32_bf16 v[116:119], v[188:191], v[148:151], v[116:119]
	v_mfma_f32_16x16x32_bf16 v[104:107], v[180:183], v[156:159], v[104:107]
	v_mfma_f32_16x16x32_bf16 v[96:99], v[188:191], v[156:159], v[96:99]
	v_mfma_f32_16x16x32_bf16 v[88:91], v[180:183], v[164:167], v[88:91]
	v_mfma_f32_16x16x32_bf16 v[80:83], v[188:191], v[164:167], v[80:83]
	v_mfma_f32_16x16x32_bf16 v[72:75], v[180:183], v[172:175], v[72:75]
	v_mfma_f32_16x16x32_bf16 v[68:71], v[188:191], v[172:175], v[68:71]
	v_mfma_f32_16x16x32_bf16 v[120:123], v[184:187], v[152:155], v[120:123]
	v_mfma_f32_16x16x32_bf16 v[116:119], v[202:205], v[152:155], v[116:119]
	v_mfma_f32_16x16x32_bf16 v[104:107], v[184:187], v[160:163], v[104:107]
	v_mfma_f32_16x16x32_bf16 v[96:99], v[202:205], v[160:163], v[96:99]
	v_mfma_f32_16x16x32_bf16 v[88:91], v[184:187], v[168:171], v[88:91]
	v_mfma_f32_16x16x32_bf16 v[80:83], v[202:205], v[168:171], v[80:83]
	v_mfma_f32_16x16x32_bf16 v[72:75], v[184:187], v[176:179], v[72:75]
	v_mfma_f32_16x16x32_bf16 v[68:71], v[202:205], v[176:179], v[68:71]
	s_barrier
; __device__ __forceinline__ int opaque_tid() { int t = threadIdx.x; asm volatile("" : "+v"(t)); return t; }
; #define PG8_STAGE(bufoff, gbase, voff) do { _Pragma("unroll") for (int _i = 0; _i < 2; ++_i) \
;         __builtin_amdgcn_global_load_lds((const unsigned*)((const char*)(gbase) + (voff)[_i]), (LAS unsigned*)(lds + (bufoff) + ldsw + _i * 8192), 16, 0, 0); } while (0)
; #define PG8_LDA(dst, b, h) do { _Pragma("unroll") for (int m = 0; m < 4; ++m) _Pragma("unroll") for (int k = 0; k < 2; ++k) dst[m][k] = *(const LAS bf16x8*)(lds + PG8_SA(b, h) + aoff + m * 2048 + k * 1024); } while (0)
; #define PG8_MMA(ai, bj, At, Bt) do { __builtin_amdgcn_s_setprio(1); _Pragma("unroll") for (int m = 0; m < 4; ++m) _Pragma("unroll") for (int n = 0; n < 2; ++n) _Pragma("unroll") for (int k = 0; k < 2; ++k) \
;         acc[ai][bj][m][n] = __builtin_amdgcn_mfma_f32_16x16x32_bf16(Bt[n][k], At[m][k], acc[ai][bj][m][n], 0, 0, 0); __builtin_amdgcn_s_setprio(0); } while (0)
; #define PG8_WAIT_V(n) asm volatile("s_waitcnt vmcnt(" #n ")" ::: "memory")
; #define PG8_WAIT_L(n) asm volatile("s_waitcnt lgkmcnt(" #n ")" ::: "memory")
; #define PG8_BAR __builtin_amdgcn_s_barrier()
; #define PG8_SCHED __builtin_amdgcn_sched_barrier(0)
;     __device__ __forceinline__ void operator()(const f32x4 (&acc)[2][2][4][2], const Unit& u, int wr, int wc, int, int) const {
;         const int ol_ = opaque_tid() & 63, fr = ol_ & 15, fq = ol_ >> 4;
;         const int row0 = u.pm * BM + wr * 64 + fr, col0 = u.pn * BM + wc * 32 + 8 * fq;
;         u32x4 cin[2][4][2];
; #pragma unroll
;         for (int ai = 0; ai < 2; ++ai)
; #pragma unroll
;             for (int m = 0; m < 4; ++m)
; #pragma unroll
;                 for (int bj = 0; bj < 2; ++bj) cin[ai][m][bj] = *(const u32x4*)(C + (size_t)(row0 + ai * HALF + m * 16) * ldc + col0 + bj * HALF);
; template <class Epi, class Sched>
; __device__ __forceinline__ void gemm_phase(LAS unsigned char* lds, const Gemm g, const Sched& S, const Epi& E) {
;     ...
;             PG8_LDA(At, 1, 1); PG8_STAGE(PG8_SA(1, 0), a3, voffA);
;             PG8_BAR; PG8_WAIT_L(0); PG8_MMA(1, 0, At, B0); PG8_BAR; PG8_SCHED;
;             PG8_STAGE(PG8_SB(1, 1), b3 + hstepB, voffB);
;             PG8_WAIT_V(6); PG8_BAR; PG8_MMA(1, 1, At, B1); PG8_BAR;
	s_setprio 0
	ds_read_b128 v[148:151], v224 offset:49152
	ds_read_b128 v[152:155], v224 offset:50176
	ds_read_b128 v[156:159], v224 offset:51200
	ds_read_b128 v[160:163], v224 offset:52224
	ds_read_b128 v[164:167], v224 offset:53248
	ds_read_b128 v[168:171], v224 offset:54272
	ds_read_b128 v[172:175], v224 offset:55296
	ds_read_b128 v[176:179], v224 offset:56320
	s_add_i32 s25, s52, s30
	v_lshl_add_u64 v[206:207], v[206:207], 0, s[8:9]
	s_mov_b32 m0, s25
	s_nop 0
	global_load_lds_dwordx4 v[206:207], off
	v_lshl_add_u64 v[206:207], v[208:209], 0, s[8:9]
	s_add_i32 m0, s25, 0x2000
	s_nop 0
	global_load_lds_dwordx4 v[206:207], off
	s_mov_b32 m0, s42
	v_lshl_add_u64 v[206:207], v[210:211], 0, s[8:9]
	global_load_lds_dwordx4 v[206:207], off
	v_lshl_add_u64 v[206:207], v[212:213], 0, s[8:9]
	s_mov_b32 m0, s43
	s_nop 0
	global_load_lds_dwordx4 v[206:207], off
	s_add_u32 s20, s20, 0x80080
	s_addc_u32 s21, s21, 0
	s_add_i32 s24, s24, s30
	s_mov_b32 m0, s24
	s_nop 0
	global_load_lds_dwordx4 v2, s[20:21]
	s_add_i32 m0, s24, 0x2000
	s_nop 0
	global_load_lds_dwordx4 v192, s[20:21]
	s_add_i32 s51, s51, 2
	s_add_u32 s6, s6, 0x100
	s_addc_u32 s7, s7, 0
	s_add_u32 s49, s49, 0x100
	s_addc_u32 s50, s50, 0
	s_cmp_gt_u32 s51, 29
	s_waitcnt lgkmcnt(0)
	s_waitcnt vmcnt(6)
	s_setprio 1
	s_barrier
	v_mfma_f32_16x16x32_bf16 v[64:67], v[132:135], v[148:151], v[64:67]
	v_mfma_f32_16x16x32_bf16 v[60:63], v[140:143], v[148:151], v[60:63]
	v_mfma_f32_16x16x32_bf16 v[52:55], v[132:135], v[156:159], v[52:55]
	v_mfma_f32_16x16x32_bf16 v[44:47], v[140:143], v[156:159], v[44:47]
	v_mfma_f32_16x16x32_bf16 v[36:39], v[132:135], v[164:167], v[36:39]
	v_mfma_f32_16x16x32_bf16 v[28:31], v[140:143], v[164:167], v[28:31]
	v_mfma_f32_16x16x32_bf16 v[20:23], v[132:135], v[172:175], v[20:23]
	v_mfma_f32_16x16x32_bf16 v[12:15], v[140:143], v[172:175], v[12:15]
	v_mfma_f32_16x16x32_bf16 v[64:67], v[136:139], v[152:155], v[64:67]
	v_mfma_f32_16x16x32_bf16 v[60:63], v[144:147], v[152:155], v[60:63]
	v_mfma_f32_16x16x32_bf16 v[52:55], v[136:139], v[160:163], v[52:55]
	v_mfma_f32_16x16x32_bf16 v[44:47], v[144:147], v[160:163], v[44:47]
	v_mfma_f32_16x16x32_bf16 v[36:39], v[136:139], v[168:171], v[36:39]
	v_mfma_f32_16x16x32_bf16 v[28:31], v[144:147], v[168:171], v[28:31]
	v_mfma_f32_16x16x32_bf16 v[20:23], v[136:139], v[176:179], v[20:23]
	v_mfma_f32_16x16x32_bf16 v[12:15], v[144:147], v[176:179], v[12:15]
	v_mfma_f32_16x16x32_bf16 v[56:59], v[180:183], v[148:151], v[56:59]
	v_mfma_f32_16x16x32_bf16 v[48:51], v[188:191], v[148:151], v[48:51]
	v_mfma_f32_16x16x32_bf16 v[40:43], v[180:183], v[156:159], v[40:43]
	v_mfma_f32_16x16x32_bf16 v[32:35], v[188:191], v[156:159], v[32:35]
	v_mfma_f32_16x16x32_bf16 v[24:27], v[180:183], v[164:167], v[24:27]
	v_mfma_f32_16x16x32_bf16 v[16:19], v[188:191], v[164:167], v[16:19]
	v_mfma_f32_16x16x32_bf16 v[8:11], v[180:183], v[172:175], v[8:11]
	v_mfma_f32_16x16x32_bf16 v[4:7], v[188:191], v[172:175], v[4:7]
	v_mfma_f32_16x16x32_bf16 v[56:59], v[184:187], v[152:155], v[56:59]
	v_mfma_f32_16x16x32_bf16 v[48:51], v[202:205], v[152:155], v[48:51]
	v_mfma_f32_16x16x32_bf16 v[40:43], v[184:187], v[160:163], v[40:43]
	v_mfma_f32_16x16x32_bf16 v[32:35], v[202:205], v[160:163], v[32:35]
	v_mfma_f32_16x16x32_bf16 v[24:27], v[184:187], v[168:171], v[24:27]
	v_mfma_f32_16x16x32_bf16 v[16:19], v[202:205], v[168:171], v[16:19]
	v_mfma_f32_16x16x32_bf16 v[8:11], v[184:187], v[176:179], v[8:11]
	v_mfma_f32_16x16x32_bf16 v[4:7], v[202:205], v[176:179], v[4:7]
	s_barrier
	s_cbranch_scc0 .LBB0_1396
	s_setprio 0
	v_mov_b32_e32 v133, v0
	s_lshl_b32 s1, s46, 8
	s_add_i32 s1, s1, s38
	v_and_or_b32 v132, v133, 15, s1
	s_lshl_b32 s1, s45, 8
	v_lshrrev_b32_e32 v133, 1, v133
	v_and_or_b32 v133, v133, 24, s1
	v_or_b32_e32 v134, s39, v133
	v_ashrrev_i32_e32 v135, 31, v134
	v_lshlrev_b64 v[202:203], 1, v[134:135]
	v_ashrrev_i32_e32 v133, 31, v132
	v_lshl_add_u64 v[134:135], s[88:89], 0, v[202:203]
	v_lshlrev_b64 v[216:217], 12, v[132:133]
	v_lshl_add_u64 v[136:137], v[134:135], 0, v[216:217]
	global_load_dwordx4 v[226:229], v[136:137], off
	global_load_dwordx4 v[188:191], v[136:137], off offset:256
	v_or_b32_e32 v136, 16, v132
	v_ashrrev_i32_e32 v137, 31, v136
	v_lshlrev_b64 v[222:223], 12, v[136:137]
	v_lshl_add_u64 v[136:137], v[134:135], 0, v[222:223]
	global_load_dwordx4 v[184:187], v[136:137], off
	global_load_dwordx4 v[180:183], v[136:137], off offset:256
	v_or_b32_e32 v136, 32, v132
	v_ashrrev_i32_e32 v137, 31, v136
	v_lshlrev_b64 v[220:221], 12, v[136:137]
	v_lshl_add_u64 v[136:137], v[134:135], 0, v[220:221]
	global_load_dwordx4 v[176:179], v[136:137], off
	global_load_dwordx4 v[168:171], v[136:137], off offset:256
	v_or_b32_e32 v132, 48, v132
	v_ashrrev_i32_e32 v133, 31, v132
	v_lshlrev_b64 v[212:213], 12, v[132:133]
	v_lshl_add_u64 v[132:133], v[134:135], 0, v[212:213]
	global_load_dwordx4 v[172:175], v[132:133], off
	global_load_dwordx4 v[164:167], v[132:133], off offset:256
	s_mov_b64 s[6:7], 0x80000
	v_lshl_add_u64 v[210:211], v[216:217], 0, s[6:7]
	v_lshl_add_u64 v[132:133], v[134:135], 0, v[210:211]
	global_load_dwordx4 v[160:163], v[132:133], off
	global_load_dwordx4 v[156:159], v[132:133], off offset:256
	s_mov_b64 s[6:7], 0x90000
	v_lshl_add_u64 v[208:209], v[216:217], 0, s[6:7]
	v_lshl_add_u64 v[132:133], v[134:135], 0, v[208:209]
	global_load_dwordx4 v[152:155], v[132:133], off
	global_load_dwordx4 v[148:151], v[132:133], off offset:256
	s_mov_b64 s[6:7], 0xa0000
	v_lshl_add_u64 v[206:207], v[216:217], 0, s[6:7]
	v_lshl_add_u64 v[132:133], v[134:135], 0, v[206:207]
	global_load_dwordx4 v[144:147], v[132:133], off
	global_load_dwordx4 v[140:143], v[132:133], off offset:256
	s_mov_b64 s[6:7], 0xb0000
	v_lshl_add_u64 v[204:205], v[216:217], 0, s[6:7]
	v_lshl_add_u64 v[132:133], v[134:135], 0, v[204:205]
	global_load_dwordx4 v[136:139], v[132:133], off
	s_nop 0
	global_load_dwordx4 v[132:135], v[132:133], off offset:256
	s_and_b64 vcc, exec, s[40:41]
	s_mov_b32 s45, s0
	s_mov_b32 s46, s14
	s_mov_b64 s[20:21], s[18:19]
	s_mov_b64 s[6:7], s[4:5]
	s_waitcnt vmcnt(15)
; __device__ __forceinline__ unsigned cvt_pk_bf16(float lo, float hi) { const f32x2 v = {lo, hi}; const bf16v2_ r = __builtin_convertvector(v, bf16v2_); return __builtin_bit_cast(unsigned, r); }
; __device__ __forceinline__ float bflo(unsigned w) { return __uint_as_float(w << 16); }
; __device__ __forceinline__ float bfhi(unsigned w) { return __uint_as_float(w & 0xffff0000u); }
;     __device__ __forceinline__ void operator()(const f32x4 (&acc)[2][2][4][2], const Unit& u, int wr, int wc, int, int) const {
;     ...
; #pragma unroll
;         for (int ai = 0; ai < 2; ++ai)
; #pragma unroll
;             for (int m = 0; m < 4; ++m)
; #pragma unroll
;                 for (int bj = 0; bj < 2; ++bj) { const u32x4 c = cin[ai][m][bj]; const f32x4 v0 = acc[ai][bj][m][0], v1 = acc[ai][bj][m][1];
;                     u32x4 w; w.x = cvt_pk_bf16(bflo(c.x) + v0[0], bfhi(c.x) + v0[1]); w.y = cvt_pk_bf16(bflo(c.y) + v0[2], bfhi(c.y) + v0[3]);
;                     w.z = cvt_pk_bf16(bflo(c.z) + v1[0], bfhi(c.z) + v1[1]); w.w = cvt_pk_bf16(bflo(c.w) + v1[2], bfhi(c.w) + v1[3]);
;                     *(u32x4*)(C + (size_t)(row0 + ai * HALF + m * 16) * ldc + col0 + bj * HALF) = w; }
	v_lshlrev_b32_e32 v218, 16, v226
	v_and_b32_e32 v219, 0xffff0000, v226
	v_pk_add_f32 v[128:129], v[128:129], v[218:219]
	v_lshlrev_b32_e32 v218, 16, v227
	v_and_b32_e32 v219, 0xffff0000, v227
	v_pk_add_f32 v[130:131], v[130:131], v[218:219]
	v_cvt_pk_bf16_f32 v128, v128, v129
	v_cvt_pk_bf16_f32 v129, v130, v131
	v_lshlrev_b32_e32 v130, 16, v228
	v_and_b32_e32 v131, 0xffff0000, v228
	v_pk_add_f32 v[124:125], v[124:125], v[130:131]
	s_nop 0
	v_cvt_pk_bf16_f32 v130, v124, v125
	v_lshlrev_b32_e32 v124, 16, v229
	v_and_b32_e32 v125, 0xffff0000, v229
	v_pk_add_f32 v[124:125], v[126:127], v[124:125]
	s_waitcnt vmcnt(14)
	v_lshlrev_b32_e32 v126, 16, v188
	v_and_b32_e32 v127, 0xffff0000, v188
	v_pk_add_f32 v[120:121], v[120:121], v[126:127]
	v_lshlrev_b32_e32 v126, 16, v189
	v_and_b32_e32 v127, 0xffff0000, v189
	v_pk_add_f32 v[122:123], v[122:123], v[126:127]
	v_cvt_pk_bf16_f32 v120, v120, v121
	v_cvt_pk_bf16_f32 v121, v122, v123
	v_lshlrev_b32_e32 v122, 16, v190
	v_and_b32_e32 v123, 0xffff0000, v190
	v_pk_add_f32 v[116:117], v[116:117], v[122:123]
	v_cvt_pk_bf16_f32 v131, v124, v125
	v_cvt_pk_bf16_f32 v122, v116, v117
	v_lshlrev_b32_e32 v116, 16, v191
	v_and_b32_e32 v117, 0xffff0000, v191
	v_pk_add_f32 v[116:117], v[118:119], v[116:117]
	v_lshl_add_u64 v[124:125], s[88:89], 0, v[216:217]
	v_cvt_pk_bf16_f32 v123, v116, v117
	s_waitcnt vmcnt(13)
	v_lshlrev_b32_e32 v116, 16, v184
	v_and_b32_e32 v117, 0xffff0000, v184
	v_pk_add_f32 v[112:113], v[112:113], v[116:117]
	v_lshlrev_b32_e32 v116, 16, v185
	v_and_b32_e32 v117, 0xffff0000, v185
	v_pk_add_f32 v[114:115], v[114:115], v[116:117]
	v_cvt_pk_bf16_f32 v112, v112, v113
	v_cvt_pk_bf16_f32 v113, v114, v115
	v_lshlrev_b32_e32 v114, 16, v186
	v_and_b32_e32 v115, 0xffff0000, v186
	v_pk_add_f32 v[108:109], v[108:109], v[114:115]
	v_lshl_add_u64 v[124:125], v[124:125], 0, v[202:203]
	v_cvt_pk_bf16_f32 v114, v108, v109
	v_lshlrev_b32_e32 v108, 16, v187
	v_and_b32_e32 v109, 0xffff0000, v187
	v_pk_add_f32 v[108:109], v[110:111], v[108:109]
	s_waitcnt vmcnt(12)
	v_lshlrev_b32_e32 v110, 16, v180
	v_and_b32_e32 v111, 0xffff0000, v180
	v_pk_add_f32 v[104:105], v[104:105], v[110:111]
	v_lshlrev_b32_e32 v110, 16, v181
	v_and_b32_e32 v111, 0xffff0000, v181
	v_pk_add_f32 v[106:107], v[106:107], v[110:111]
	v_cvt_pk_bf16_f32 v104, v104, v105
	v_cvt_pk_bf16_f32 v105, v106, v107
	v_lshlrev_b32_e32 v106, 16, v182
	v_and_b32_e32 v107, 0xffff0000, v182
	v_pk_add_f32 v[96:97], v[96:97], v[106:107]
	v_cvt_pk_bf16_f32 v115, v108, v109
	v_cvt_pk_bf16_f32 v106, v96, v97
	v_lshlrev_b32_e32 v96, 16, v183
	v_and_b32_e32 v97, 0xffff0000, v183
	v_pk_add_f32 v[96:97], v[98:99], v[96:97]
	s_waitcnt vmcnt(11)
	v_lshlrev_b32_e32 v98, 16, v177
	v_cvt_pk_bf16_f32 v107, v96, v97
	v_lshlrev_b32_e32 v96, 16, v176
	v_and_b32_e32 v97, 0xffff0000, v176
	v_and_b32_e32 v99, 0xffff0000, v177
	v_pk_add_f32 v[96:97], v[100:101], v[96:97]
	v_pk_add_f32 v[98:99], v[102:103], v[98:99]
	v_cvt_pk_bf16_f32 v96, v96, v97
	v_cvt_pk_bf16_f32 v97, v98, v99
	v_lshlrev_b32_e32 v98, 16, v178
	v_and_b32_e32 v99, 0xffff0000, v178
	v_pk_add_f32 v[92:93], v[92:93], v[98:99]
	v_lshl_add_u64 v[108:109], s[88:89], 0, v[222:223]
	v_cvt_pk_bf16_f32 v98, v92, v93
	v_lshlrev_b32_e32 v92, 16, v179
	v_and_b32_e32 v93, 0xffff0000, v179
	v_pk_add_f32 v[92:93], v[94:95], v[92:93]
	s_waitcnt vmcnt(10)
	v_lshlrev_b32_e32 v94, 16, v168
	v_and_b32_e32 v95, 0xffff0000, v168
	v_pk_add_f32 v[88:89], v[88:89], v[94:95]
	v_lshlrev_b32_e32 v94, 16, v169
	v_and_b32_e32 v95, 0xffff0000, v169
	v_pk_add_f32 v[90:91], v[90:91], v[94:95]
	v_cvt_pk_bf16_f32 v88, v88, v89
	v_cvt_pk_bf16_f32 v89, v90, v91
	v_lshlrev_b32_e32 v90, 16, v170
	v_and_b32_e32 v91, 0xffff0000, v170
	v_pk_add_f32 v[80:81], v[80:81], v[90:91]
	v_cvt_pk_bf16_f32 v99, v92, v93
	v_cvt_pk_bf16_f32 v90, v80, v81
	v_lshlrev_b32_e32 v80, 16, v171
	v_and_b32_e32 v81, 0xffff0000, v171
	v_pk_add_f32 v[80:81], v[82:83], v[80:81]
	s_waitcnt vmcnt(9)
	v_lshlrev_b32_e32 v82, 16, v173
	v_cvt_pk_bf16_f32 v91, v80, v81
	v_lshlrev_b32_e32 v80, 16, v172
	v_and_b32_e32 v81, 0xffff0000, v172
	v_and_b32_e32 v83, 0xffff0000, v173
	v_pk_add_f32 v[80:81], v[84:85], v[80:81]
	v_pk_add_f32 v[82:83], v[86:87], v[82:83]
	v_cvt_pk_bf16_f32 v80, v80, v81
	v_cvt_pk_bf16_f32 v81, v82, v83
	v_lshlrev_b32_e32 v82, 16, v174
	v_and_b32_e32 v83, 0xffff0000, v174
	v_pk_add_f32 v[76:77], v[76:77], v[82:83]
	v_lshl_add_u64 v[92:93], s[88:89], 0, v[220:221]
	v_cvt_pk_bf16_f32 v82, v76, v77
	v_lshlrev_b32_e32 v76, 16, v175
	v_and_b32_e32 v77, 0xffff0000, v175
	v_pk_add_f32 v[76:77], v[78:79], v[76:77]
	s_waitcnt vmcnt(8)
	v_lshlrev_b32_e32 v78, 16, v164
	v_and_b32_e32 v79, 0xffff0000, v164
	v_pk_add_f32 v[72:73], v[72:73], v[78:79]
	v_lshlrev_b32_e32 v78, 16, v165
	v_and_b32_e32 v79, 0xffff0000, v165
	v_pk_add_f32 v[74:75], v[74:75], v[78:79]
	v_cvt_pk_bf16_f32 v72, v72, v73
	v_cvt_pk_bf16_f32 v73, v74, v75
	v_lshlrev_b32_e32 v74, 16, v166
	v_and_b32_e32 v75, 0xffff0000, v166
	v_pk_add_f32 v[68:69], v[68:69], v[74:75]
	v_cvt_pk_bf16_f32 v83, v76, v77
	v_cvt_pk_bf16_f32 v74, v68, v69
	v_lshlrev_b32_e32 v68, 16, v167
	v_and_b32_e32 v69, 0xffff0000, v167
	v_pk_add_f32 v[68:69], v[70:71], v[68:69]
	v_lshl_add_u64 v[76:77], s[88:89], 0, v[212:213]
	v_cvt_pk_bf16_f32 v75, v68, v69
	s_waitcnt vmcnt(7)
	v_lshlrev_b32_e32 v68, 16, v160
	v_and_b32_e32 v69, 0xffff0000, v160
	v_pk_add_f32 v[64:65], v[64:65], v[68:69]
	v_lshlrev_b32_e32 v68, 16, v161
	v_and_b32_e32 v69, 0xffff0000, v161
	v_pk_add_f32 v[66:67], v[66:67], v[68:69]
	v_cvt_pk_bf16_f32 v64, v64, v65
	v_cvt_pk_bf16_f32 v65, v66, v67
	v_lshlrev_b32_e32 v66, 16, v162
	v_and_b32_e32 v67, 0xffff0000, v162
	v_pk_add_f32 v[60:61], v[60:61], v[66:67]
	v_lshl_add_u64 v[108:109], v[108:109], 0, v[202:203]
	v_cvt_pk_bf16_f32 v66, v60, v61
	v_lshlrev_b32_e32 v60, 16, v163
	v_and_b32_e32 v61, 0xffff0000, v163
	v_pk_add_f32 v[60:61], v[62:63], v[60:61]
	s_waitcnt vmcnt(6)
; __device__ __forceinline__ unsigned cvt_pk_bf16(float lo, float hi) { const f32x2 v = {lo, hi}; const bf16v2_ r = __builtin_convertvector(v, bf16v2_); return __builtin_bit_cast(unsigned, r); }
; __device__ __forceinline__ float bflo(unsigned w) { return __uint_as_float(w << 16); }
; __device__ __forceinline__ float bfhi(unsigned w) { return __uint_as_float(w & 0xffff0000u); }
; #define PG8_WAIT_V(n) asm volatile("s_waitcnt vmcnt(" #n ")" ::: "memory")
; #define PG8_BAR __builtin_amdgcn_s_barrier()
;     __device__ __forceinline__ void operator()(const f32x4 (&acc)[2][2][4][2], const Unit& u, int wr, int wc, int, int) const {
;     ...
;                 for (int bj = 0; bj < 2; ++bj) { const u32x4 c = cin[ai][m][bj]; const f32x4 v0 = acc[ai][bj][m][0], v1 = acc[ai][bj][m][1];
;                     u32x4 w; w.x = cvt_pk_bf16(bflo(c.x) + v0[0], bfhi(c.x) + v0[1]); w.y = cvt_pk_bf16(bflo(c.y) + v0[2], bfhi(c.y) + v0[3]);
;                     w.z = cvt_pk_bf16(bflo(c.z) + v1[0], bfhi(c.z) + v1[1]); w.w = cvt_pk_bf16(bflo(c.w) + v1[2], bfhi(c.w) + v1[3]);
;                     *(u32x4*)(C + (size_t)(row0 + ai * HALF + m * 16) * ldc + col0 + bj * HALF) = w; }
; template <class Epi, class Sched>
; __device__ __forceinline__ void gemm_phase(LAS unsigned char* lds, const Gemm g, const Sched& S, const Epi& E) {
;     ...
;     PG8_WAIT_V(0);
;     if (wr == 0) PG8_BAR;
;     PG8_BAR;
	v_lshlrev_b32_e32 v62, 16, v156
	v_and_b32_e32 v63, 0xffff0000, v156
	v_pk_add_f32 v[56:57], v[56:57], v[62:63]
	v_lshlrev_b32_e32 v62, 16, v157
	v_and_b32_e32 v63, 0xffff0000, v157
	v_pk_add_f32 v[58:59], v[58:59], v[62:63]
	v_cvt_pk_bf16_f32 v56, v56, v57
	v_cvt_pk_bf16_f32 v57, v58, v59
	v_lshlrev_b32_e32 v58, 16, v158
	v_and_b32_e32 v59, 0xffff0000, v158
	v_pk_add_f32 v[48:49], v[48:49], v[58:59]
	v_cvt_pk_bf16_f32 v67, v60, v61
	v_cvt_pk_bf16_f32 v58, v48, v49
	v_lshlrev_b32_e32 v48, 16, v159
	v_and_b32_e32 v49, 0xffff0000, v159
	v_pk_add_f32 v[48:49], v[50:51], v[48:49]
	s_waitcnt vmcnt(5)
	v_lshlrev_b32_e32 v50, 16, v153
	v_cvt_pk_bf16_f32 v59, v48, v49
	v_lshlrev_b32_e32 v48, 16, v152
	v_and_b32_e32 v49, 0xffff0000, v152
	v_and_b32_e32 v51, 0xffff0000, v153
	v_pk_add_f32 v[48:49], v[52:53], v[48:49]
	v_pk_add_f32 v[50:51], v[54:55], v[50:51]
	v_cvt_pk_bf16_f32 v48, v48, v49
	v_cvt_pk_bf16_f32 v49, v50, v51
	v_lshlrev_b32_e32 v50, 16, v154
	v_and_b32_e32 v51, 0xffff0000, v154
	v_pk_add_f32 v[44:45], v[44:45], v[50:51]
	v_lshl_add_u64 v[60:61], s[88:89], 0, v[210:211]
	v_cvt_pk_bf16_f32 v50, v44, v45
	v_lshlrev_b32_e32 v44, 16, v155
	v_and_b32_e32 v45, 0xffff0000, v155
	v_pk_add_f32 v[44:45], v[46:47], v[44:45]
	s_waitcnt vmcnt(4)
	v_lshlrev_b32_e32 v46, 16, v148
	v_and_b32_e32 v47, 0xffff0000, v148
	v_pk_add_f32 v[40:41], v[40:41], v[46:47]
	v_lshlrev_b32_e32 v46, 16, v149
	v_and_b32_e32 v47, 0xffff0000, v149
	v_pk_add_f32 v[42:43], v[42:43], v[46:47]
	v_cvt_pk_bf16_f32 v40, v40, v41
	v_cvt_pk_bf16_f32 v41, v42, v43
	v_lshlrev_b32_e32 v42, 16, v150
	v_and_b32_e32 v43, 0xffff0000, v150
	v_pk_add_f32 v[32:33], v[32:33], v[42:43]
	v_cvt_pk_bf16_f32 v51, v44, v45
	v_cvt_pk_bf16_f32 v42, v32, v33
	v_lshlrev_b32_e32 v32, 16, v151
	v_and_b32_e32 v33, 0xffff0000, v151
	v_pk_add_f32 v[32:33], v[34:35], v[32:33]
	s_waitcnt vmcnt(3)
	v_lshlrev_b32_e32 v34, 16, v145
	v_cvt_pk_bf16_f32 v43, v32, v33
	v_lshlrev_b32_e32 v32, 16, v144
	v_and_b32_e32 v33, 0xffff0000, v144
	v_and_b32_e32 v35, 0xffff0000, v145
	v_pk_add_f32 v[32:33], v[36:37], v[32:33]
	v_pk_add_f32 v[34:35], v[38:39], v[34:35]
	v_cvt_pk_bf16_f32 v32, v32, v33
	v_cvt_pk_bf16_f32 v33, v34, v35
	v_lshlrev_b32_e32 v34, 16, v146
	v_and_b32_e32 v35, 0xffff0000, v146
	v_pk_add_f32 v[28:29], v[28:29], v[34:35]
	v_lshl_add_u64 v[44:45], s[88:89], 0, v[208:209]
	v_cvt_pk_bf16_f32 v34, v28, v29
	v_lshlrev_b32_e32 v28, 16, v147
	v_and_b32_e32 v29, 0xffff0000, v147
	v_pk_add_f32 v[28:29], v[30:31], v[28:29]
	s_waitcnt vmcnt(2)
	v_lshlrev_b32_e32 v30, 16, v140
	v_and_b32_e32 v31, 0xffff0000, v140
	v_pk_add_f32 v[24:25], v[24:25], v[30:31]
	v_lshlrev_b32_e32 v30, 16, v141
	v_and_b32_e32 v31, 0xffff0000, v141
	v_pk_add_f32 v[26:27], v[26:27], v[30:31]
	v_cvt_pk_bf16_f32 v24, v24, v25
	v_cvt_pk_bf16_f32 v25, v26, v27
	v_lshlrev_b32_e32 v26, 16, v142
	v_and_b32_e32 v27, 0xffff0000, v142
	v_pk_add_f32 v[16:17], v[16:17], v[26:27]
	v_cvt_pk_bf16_f32 v35, v28, v29
	v_cvt_pk_bf16_f32 v26, v16, v17
	v_lshlrev_b32_e32 v16, 16, v143
	v_and_b32_e32 v17, 0xffff0000, v143
	v_pk_add_f32 v[16:17], v[18:19], v[16:17]
	s_waitcnt vmcnt(1)
	v_lshlrev_b32_e32 v18, 16, v137
	v_cvt_pk_bf16_f32 v27, v16, v17
	v_lshlrev_b32_e32 v16, 16, v136
	v_and_b32_e32 v17, 0xffff0000, v136
	v_and_b32_e32 v19, 0xffff0000, v137
	v_pk_add_f32 v[16:17], v[20:21], v[16:17]
	v_pk_add_f32 v[18:19], v[22:23], v[18:19]
	v_cvt_pk_bf16_f32 v16, v16, v17
	v_cvt_pk_bf16_f32 v17, v18, v19
	v_lshlrev_b32_e32 v18, 16, v138
	v_and_b32_e32 v19, 0xffff0000, v138
	v_pk_add_f32 v[12:13], v[12:13], v[18:19]
	v_lshl_add_u64 v[28:29], s[88:89], 0, v[206:207]
	v_cvt_pk_bf16_f32 v18, v12, v13
	v_lshlrev_b32_e32 v12, 16, v139
	v_and_b32_e32 v13, 0xffff0000, v139
	v_pk_add_f32 v[12:13], v[14:15], v[12:13]
	s_waitcnt vmcnt(0)
	v_lshlrev_b32_e32 v14, 16, v132
	v_and_b32_e32 v15, 0xffff0000, v132
	v_pk_add_f32 v[8:9], v[8:9], v[14:15]
	v_lshlrev_b32_e32 v14, 16, v133
	v_and_b32_e32 v15, 0xffff0000, v133
	v_pk_add_f32 v[10:11], v[10:11], v[14:15]
	v_cvt_pk_bf16_f32 v8, v8, v9
	v_cvt_pk_bf16_f32 v9, v10, v11
	v_lshlrev_b32_e32 v10, 16, v134
	v_and_b32_e32 v11, 0xffff0000, v134
	v_pk_add_f32 v[4:5], v[4:5], v[10:11]
	v_cvt_pk_bf16_f32 v19, v12, v13
	v_cvt_pk_bf16_f32 v10, v4, v5
	v_lshlrev_b32_e32 v4, 16, v135
	v_and_b32_e32 v5, 0xffff0000, v135
	v_lshl_add_u64 v[12:13], s[88:89], 0, v[204:205]
	v_pk_add_f32 v[4:5], v[6:7], v[4:5]
	v_lshl_add_u64 v[92:93], v[92:93], 0, v[202:203]
	v_lshl_add_u64 v[76:77], v[76:77], 0, v[202:203]
	v_lshl_add_u64 v[60:61], v[60:61], 0, v[202:203]
	v_lshl_add_u64 v[44:45], v[44:45], 0, v[202:203]
	v_lshl_add_u64 v[28:29], v[28:29], 0, v[202:203]
	v_lshl_add_u64 v[12:13], v[12:13], 0, v[202:203]
	v_cvt_pk_bf16_f32 v11, v4, v5
	global_store_dwordx4 v[124:125], v[128:131], off
	global_store_dwordx4 v[124:125], v[120:123], off offset:256
	global_store_dwordx4 v[108:109], v[112:115], off
	global_store_dwordx4 v[108:109], v[104:107], off offset:256
	global_store_dwordx4 v[92:93], v[96:99], off
	global_store_dwordx4 v[92:93], v[88:91], off offset:256
	global_store_dwordx4 v[76:77], v[80:83], off
	global_store_dwordx4 v[76:77], v[72:75], off offset:256
	global_store_dwordx4 v[60:61], v[64:67], off
	global_store_dwordx4 v[60:61], v[56:59], off offset:256
	global_store_dwordx4 v[44:45], v[48:51], off
	global_store_dwordx4 v[44:45], v[40:43], off offset:256
	global_store_dwordx4 v[28:29], v[32:35], off
	global_store_dwordx4 v[28:29], v[24:27], off offset:256
	global_store_dwordx4 v[12:13], v[16:19], off
	global_store_dwordx4 v[12:13], v[8:11], off offset:256
	s_cbranch_vccz .LBB0_1389
	s_waitcnt vmcnt(0)
	s_cmpk_gt_u32 s2, 0xff
	s_cbranch_scc1 .LBB0_1400
	s_barrier

; #define PG8_STAGE(bufoff, gbase, voff) do { _Pragma("unroll") for (int _i = 0; _i < 2; ++_i) \
;         __builtin_amdgcn_global_load_lds((const unsigned*)((const char*)(gbase) + (voff)[_i]), (LAS unsigned*)(lds + (bufoff) + ldsw + _i * 8192), 16, 0, 0); } while (0)
; #define PG8_LDA(dst, b, h) do { _Pragma("unroll") for (int m = 0; m < 4; ++m) _Pragma("unroll") for (int k = 0; k < 2; ++k) dst[m][k] = *(const LAS bf16x8*)(lds + PG8_SA(b, h) + aoff + m * 2048 + k * 1024); } while (0)
; #define PG8_LDB(dst, b, h) do { _Pragma("unroll") for (int n = 0; n < 2; ++n) _Pragma("unroll") for (int k = 0; k < 2; ++k) dst[n][k] = *(const LAS bf16x8*)(lds + PG8_SB(b, h) + boff + n * 2048 + k * 1024); } while (0)
; #define PG8_MMA(ai, bj, At, Bt) do { __builtin_amdgcn_s_setprio(1); _Pragma("unroll") for (int m = 0; m < 4; ++m) _Pragma("unroll") for (int n = 0; n < 2; ++n) _Pragma("unroll") for (int k = 0; k < 2; ++k) \
;         acc[ai][bj][m][n] = __builtin_amdgcn_mfma_f32_16x16x32_bf16(Bt[n][k], At[m][k], acc[ai][bj][m][n], 0, 0, 0); __builtin_amdgcn_s_setprio(0); } while (0)
; #define PG8_WAIT_V(n) asm volatile("s_waitcnt vmcnt(" #n ")" ::: "memory")
; #define PG8_BAR __builtin_amdgcn_s_barrier()
; template <class Epi, class Sched>
; __device__ __forceinline__ void gemm_phase(LAS unsigned char* lds, const Gemm g, const Sched& S, const Epi& E) {
;     ...
;         for (int t = 0; t < nt; t += 2) {
;             const bool last = (t == nt - 2);
;             const char* a1 = cA + (size_t)(t + 1) * kstep;
;             const char* a2 = last ? nA : cA + (size_t)(t + 2) * kstep; const char* b2 = last ? nB : cB + (size_t)(t + 2) * kstep;
;             const char* a3 = a2 + kstep; const char* b3 = b2 + kstep;
;             if (last && has_next) S.a_ready(nxt);
;             PG8_LDB(B0, 0, 0); PG8_SCHED; PG8_LDA(At, 0, 0); PG8_STAGE(PG8_SA(1, 1), a1 + hstepA, voffA);
;             PG8_WAIT_L(8); PG8_BAR; PG8_WAIT_L(0); PG8_MMA(0, 0, At, B0); PG8_BAR; PG8_SCHED;
;             PG8_LDB(B1, 0, 1); PG8_STAGE(PG8_SB(0, 0), b2, voffB);
;             PG8_BAR; PG8_WAIT_L(0); PG8_MMA(0, 1, At, B1); PG8_BAR;
;             PG8_LDA(At, 0, 1); PG8_STAGE(PG8_SA(0, 0), a2, voffA);
;             PG8_BAR; PG8_WAIT_L(0); PG8_MMA(1, 0, At, B0); PG8_BAR; PG8_SCHED;
;             PG8_STAGE(PG8_SB(0, 1), b2 + hstepB, voffB);
;             PG8_WAIT_V(6); PG8_BAR; PG8_MMA(1, 1, At, B1); PG8_BAR;
.LBB0_1666:
	s_setprio 0
	s_add_u32 s14, s6, 0x100
	s_addc_u32 s15, s7, 0
	s_add_i32 s45, 0, 0x10000
	v_add_u32_e32 v144, s45, v1
	ds_read_b128 v[132:135], v144
	ds_read_b128 v[136:139], v144 offset:1024
	ds_read_b128 v[140:143], v144 offset:2048
	ds_read_b128 v[144:147], v144 offset:3072
	s_cmpk_eq_i32 s44, 0x54
	s_cselect_b32 s21, s1, s15
	s_cselect_b32 s20, s0, s14
	s_cselect_b32 s19, s5, s43
	s_cselect_b32 s18, s4, s42
	ds_read_b128 v[148:151], v224
	ds_read_b128 v[152:155], v224 offset:1024
	ds_read_b128 v[156:159], v224 offset:2048
	ds_read_b128 v[160:163], v224 offset:3072
	ds_read_b128 v[164:167], v224 offset:4096
	ds_read_b128 v[168:171], v224 offset:5120
	ds_read_b128 v[172:175], v224 offset:6144
	ds_read_b128 v[176:179], v224 offset:7168
	s_add_i32 s51, 0, 0x14000
	v_add_u32_e32 v202, s51, v1
	ds_read_b128 v[180:183], v202
	ds_read_b128 v[184:187], v202 offset:1024
	ds_read_b128 v[188:191], v202 offset:2048
	ds_read_b128 v[202:205], v202 offset:3072
	s_add_i32 m0, s29, 0xc000
	s_nop 0
	global_load_lds_dwordx4 v198, s[6:7]
	s_add_i32 m0, s29, 0xe000
	s_nop 0
	global_load_lds_dwordx4 v200, s[6:7]
	s_waitcnt lgkmcnt(0)
	s_setprio 1
	s_barrier
	v_mfma_f32_16x16x32_bf16 v[128:131], v[132:135], v[148:151], v[128:131]
	v_mfma_f32_16x16x32_bf16 v[124:127], v[140:143], v[148:151], v[124:127]
	v_mfma_f32_16x16x32_bf16 v[112:115], v[132:135], v[156:159], v[112:115]
	v_mfma_f32_16x16x32_bf16 v[108:111], v[140:143], v[156:159], v[108:111]
	v_mfma_f32_16x16x32_bf16 v[100:103], v[132:135], v[164:167], v[100:103]
	v_mfma_f32_16x16x32_bf16 v[92:95], v[140:143], v[164:167], v[92:95]
	v_mfma_f32_16x16x32_bf16 v[84:87], v[132:135], v[172:175], v[84:87]
	v_mfma_f32_16x16x32_bf16 v[76:79], v[140:143], v[172:175], v[76:79]
	v_mfma_f32_16x16x32_bf16 v[128:131], v[136:139], v[152:155], v[128:131]
	v_mfma_f32_16x16x32_bf16 v[124:127], v[144:147], v[152:155], v[124:127]
	v_mfma_f32_16x16x32_bf16 v[112:115], v[136:139], v[160:163], v[112:115]
	v_mfma_f32_16x16x32_bf16 v[108:111], v[144:147], v[160:163], v[108:111]
	v_mfma_f32_16x16x32_bf16 v[100:103], v[136:139], v[168:171], v[100:103]
	v_mfma_f32_16x16x32_bf16 v[92:95], v[144:147], v[168:171], v[92:95]
	v_mfma_f32_16x16x32_bf16 v[84:87], v[136:139], v[176:179], v[84:87]
	v_mfma_f32_16x16x32_bf16 v[76:79], v[144:147], v[176:179], v[76:79]
	v_mfma_f32_16x16x32_bf16 v[120:123], v[180:183], v[148:151], v[120:123]
	v_mfma_f32_16x16x32_bf16 v[116:119], v[188:191], v[148:151], v[116:119]
	v_mfma_f32_16x16x32_bf16 v[104:107], v[180:183], v[156:159], v[104:107]
	v_mfma_f32_16x16x32_bf16 v[96:99], v[188:191], v[156:159], v[96:99]
	v_mfma_f32_16x16x32_bf16 v[88:91], v[180:183], v[164:167], v[88:91]
	v_mfma_f32_16x16x32_bf16 v[80:83], v[188:191], v[164:167], v[80:83]
	v_mfma_f32_16x16x32_bf16 v[72:75], v[180:183], v[172:175], v[72:75]
	v_mfma_f32_16x16x32_bf16 v[68:71], v[188:191], v[172:175], v[68:71]
	v_mfma_f32_16x16x32_bf16 v[120:123], v[184:187], v[152:155], v[120:123]
	v_mfma_f32_16x16x32_bf16 v[116:119], v[202:205], v[152:155], v[116:119]
	v_mfma_f32_16x16x32_bf16 v[104:107], v[184:187], v[160:163], v[104:107]
	v_mfma_f32_16x16x32_bf16 v[96:99], v[202:205], v[160:163], v[96:99]
	v_mfma_f32_16x16x32_bf16 v[88:91], v[184:187], v[168:171], v[88:91]
	v_mfma_f32_16x16x32_bf16 v[80:83], v[202:205], v[168:171], v[80:83]
	v_mfma_f32_16x16x32_bf16 v[72:75], v[184:187], v[176:179], v[72:75]
	v_mfma_f32_16x16x32_bf16 v[68:71], v[202:205], v[176:179], v[68:71]
	s_barrier
	s_setprio 0
	ds_read_b128 v[148:151], v224 offset:16384
	ds_read_b128 v[152:155], v224 offset:17408
	ds_read_b128 v[156:159], v224 offset:18432
	ds_read_b128 v[160:163], v224 offset:19456
	ds_read_b128 v[164:167], v224 offset:20480
	ds_read_b128 v[168:171], v224 offset:21504
	ds_read_b128 v[172:175], v224 offset:22528
	ds_read_b128 v[176:179], v224 offset:23552
	s_add_i32 s6, s45, s28
	v_lshl_add_u64 v[206:207], s[18:19], 0, v[2:3]
	s_mov_b32 m0, s6
	s_nop 0
	global_load_lds_dwordx4 v[206:207], off
	v_lshl_add_u64 v[208:209], s[18:19], 0, v[192:193]
	s_add_i32 m0, s6, 0x2000
	s_nop 0
	global_load_lds_dwordx4 v[208:209], off
	s_mov_b32 m0, s29
	v_lshl_add_u64 v[210:211], s[20:21], 0, v[196:197]
	global_load_lds_dwordx4 v[210:211], off
	v_lshl_add_u64 v[212:213], s[20:21], 0, v[194:195]
	s_mov_b32 m0, s30
	s_nop 0
	global_load_lds_dwordx4 v[212:213], off
	s_add_u32 s6, s18, 0x160000
	s_addc_u32 s7, s19, 0
	s_add_i32 s45, s51, s28
	s_mov_b32 m0, s45
	s_nop 0
	global_load_lds_dwordx4 v2, s[6:7]
	s_add_i32 m0, s45, 0x2000
	s_nop 0
	global_load_lds_dwordx4 v192, s[6:7]
	s_waitcnt lgkmcnt(0)
	s_waitcnt vmcnt(6)
	s_setprio 1
	s_barrier
; #define PG8_STAGE(bufoff, gbase, voff) do { _Pragma("unroll") for (int _i = 0; _i < 2; ++_i) \
;         __builtin_amdgcn_global_load_lds((const unsigned*)((const char*)(gbase) + (voff)[_i]), (LAS unsigned*)(lds + (bufoff) + ldsw + _i * 8192), 16, 0, 0); } while (0)
; #define PG8_LDA(dst, b, h) do { _Pragma("unroll") for (int m = 0; m < 4; ++m) _Pragma("unroll") for (int k = 0; k < 2; ++k) dst[m][k] = *(const LAS bf16x8*)(lds + PG8_SA(b, h) + aoff + m * 2048 + k * 1024); } while (0)
; #define PG8_LDB(dst, b, h) do { _Pragma("unroll") for (int n = 0; n < 2; ++n) _Pragma("unroll") for (int k = 0; k < 2; ++k) dst[n][k] = *(const LAS bf16x8*)(lds + PG8_SB(b, h) + boff + n * 2048 + k * 1024); } while (0)
; #define PG8_MMA(ai, bj, At, Bt) do { __builtin_amdgcn_s_setprio(1); _Pragma("unroll") for (int m = 0; m < 4; ++m) _Pragma("unroll") for (int n = 0; n < 2; ++n) _Pragma("unroll") for (int k = 0; k < 2; ++k) \
;         acc[ai][bj][m][n] = __builtin_amdgcn_mfma_f32_16x16x32_bf16(Bt[n][k], At[m][k], acc[ai][bj][m][n], 0, 0, 0); __builtin_amdgcn_s_setprio(0); } while (0)
; #define PG8_WAIT_V(n) asm volatile("s_waitcnt vmcnt(" #n ")" ::: "memory")
; #define PG8_WAIT_L(n) asm volatile("s_waitcnt lgkmcnt(" #n ")" ::: "memory")
; #define PG8_BAR __builtin_amdgcn_s_barrier()
; #define PG8_SCHED __builtin_amdgcn_sched_barrier(0)
; template <class Epi, class Sched>
; __device__ __forceinline__ void gemm_phase(LAS unsigned char* lds, const Gemm g, const Sched& S, const Epi& E) {
;     ...
;             PG8_WAIT_V(6); PG8_BAR; PG8_MMA(1, 1, At, B1); PG8_BAR;
;             PG8_LDB(B0, 1, 0); PG8_SCHED; PG8_LDA(At, 1, 0); PG8_STAGE(PG8_SA(0, 1), a2 + hstepA, voffA);
;             PG8_WAIT_L(8); PG8_BAR; PG8_WAIT_L(0); PG8_MMA(0, 0, At, B0); PG8_BAR; PG8_SCHED;
;             PG8_LDB(B1, 1, 1); PG8_STAGE(PG8_SB(1, 0), b3, voffB);
;             PG8_BAR; PG8_WAIT_L(0); PG8_MMA(0, 1, At, B1); PG8_BAR;
;             PG8_LDA(At, 1, 1); PG8_STAGE(PG8_SA(1, 0), a3, voffA);
;             PG8_BAR; PG8_WAIT_L(0); PG8_MMA(1, 0, At, B0); PG8_BAR; PG8_SCHED;
	v_mfma_f32_16x16x32_bf16 v[64:67], v[132:135], v[148:151], v[64:67]
	v_mfma_f32_16x16x32_bf16 v[60:63], v[140:143], v[148:151], v[60:63]
	v_mfma_f32_16x16x32_bf16 v[52:55], v[132:135], v[156:159], v[52:55]
	v_mfma_f32_16x16x32_bf16 v[44:47], v[140:143], v[156:159], v[44:47]
	v_mfma_f32_16x16x32_bf16 v[36:39], v[132:135], v[164:167], v[36:39]
	v_mfma_f32_16x16x32_bf16 v[28:31], v[140:143], v[164:167], v[28:31]
	v_mfma_f32_16x16x32_bf16 v[20:23], v[132:135], v[172:175], v[20:23]
	v_mfma_f32_16x16x32_bf16 v[12:15], v[140:143], v[172:175], v[12:15]
	v_mfma_f32_16x16x32_bf16 v[64:67], v[136:139], v[152:155], v[64:67]
	v_mfma_f32_16x16x32_bf16 v[60:63], v[144:147], v[152:155], v[60:63]
	v_mfma_f32_16x16x32_bf16 v[52:55], v[136:139], v[160:163], v[52:55]
	v_mfma_f32_16x16x32_bf16 v[44:47], v[144:147], v[160:163], v[44:47]
	v_mfma_f32_16x16x32_bf16 v[36:39], v[136:139], v[168:171], v[36:39]
	v_mfma_f32_16x16x32_bf16 v[28:31], v[144:147], v[168:171], v[28:31]
	v_mfma_f32_16x16x32_bf16 v[20:23], v[136:139], v[176:179], v[20:23]
	v_mfma_f32_16x16x32_bf16 v[12:15], v[144:147], v[176:179], v[12:15]
	v_mfma_f32_16x16x32_bf16 v[56:59], v[180:183], v[148:151], v[56:59]
	v_mfma_f32_16x16x32_bf16 v[48:51], v[188:191], v[148:151], v[48:51]
	v_mfma_f32_16x16x32_bf16 v[40:43], v[180:183], v[156:159], v[40:43]
	v_mfma_f32_16x16x32_bf16 v[32:35], v[188:191], v[156:159], v[32:35]
	v_mfma_f32_16x16x32_bf16 v[24:27], v[180:183], v[164:167], v[24:27]
	v_mfma_f32_16x16x32_bf16 v[16:19], v[188:191], v[164:167], v[16:19]
	v_mfma_f32_16x16x32_bf16 v[8:11], v[180:183], v[172:175], v[8:11]
	v_mfma_f32_16x16x32_bf16 v[4:7], v[188:191], v[172:175], v[4:7]
	v_mfma_f32_16x16x32_bf16 v[56:59], v[184:187], v[152:155], v[56:59]
	v_mfma_f32_16x16x32_bf16 v[48:51], v[202:205], v[152:155], v[48:51]
	v_mfma_f32_16x16x32_bf16 v[40:43], v[184:187], v[160:163], v[40:43]
	v_mfma_f32_16x16x32_bf16 v[32:35], v[202:205], v[160:163], v[32:35]
	v_mfma_f32_16x16x32_bf16 v[24:27], v[184:187], v[168:171], v[24:27]
	v_mfma_f32_16x16x32_bf16 v[16:19], v[202:205], v[168:171], v[16:19]
	v_mfma_f32_16x16x32_bf16 v[8:11], v[184:187], v[176:179], v[8:11]
	v_mfma_f32_16x16x32_bf16 v[4:7], v[202:205], v[176:179], v[4:7]
	s_barrier
	s_setprio 0
	s_add_i32 s45, 0, 0x18000
	v_add_u32_e32 v144, s45, v1
	ds_read_b128 v[132:135], v144
	ds_read_b128 v[136:139], v144 offset:1024
	ds_read_b128 v[140:143], v144 offset:2048
	ds_read_b128 v[144:147], v144 offset:3072
	s_add_u32 s6, s20, 0x160000
	s_addc_u32 s7, s21, 0
	ds_read_b128 v[148:151], v224 offset:32768
	ds_read_b128 v[152:155], v224 offset:33792
	ds_read_b128 v[156:159], v224 offset:34816
	ds_read_b128 v[160:163], v224 offset:35840
	ds_read_b128 v[164:167], v224 offset:36864
	ds_read_b128 v[168:171], v224 offset:37888
	ds_read_b128 v[172:175], v224 offset:38912
	ds_read_b128 v[176:179], v224 offset:39936
	s_mov_b32 m0, s31
	s_nop 0
	global_load_lds_dwordx4 v196, s[6:7]
	s_mov_b32 m0, s35
	s_nop 0
	global_load_lds_dwordx4 v194, s[6:7]
	s_add_i32 s20, 0, 0x1c000
	v_add_u32_e32 v202, s20, v1
	ds_read_b128 v[180:183], v202
	ds_read_b128 v[184:187], v202 offset:1024
	ds_read_b128 v[188:191], v202 offset:2048
	ds_read_b128 v[202:205], v202 offset:3072
	s_waitcnt lgkmcnt(0)
	s_setprio 1
	s_barrier
	v_mfma_f32_16x16x32_bf16 v[128:131], v[132:135], v[148:151], v[128:131]
	v_mfma_f32_16x16x32_bf16 v[124:127], v[140:143], v[148:151], v[124:127]
	v_mfma_f32_16x16x32_bf16 v[112:115], v[132:135], v[156:159], v[112:115]
	v_mfma_f32_16x16x32_bf16 v[108:111], v[140:143], v[156:159], v[108:111]
	v_mfma_f32_16x16x32_bf16 v[100:103], v[132:135], v[164:167], v[100:103]
	v_mfma_f32_16x16x32_bf16 v[92:95], v[140:143], v[164:167], v[92:95]
	v_mfma_f32_16x16x32_bf16 v[84:87], v[132:135], v[172:175], v[84:87]
	v_mfma_f32_16x16x32_bf16 v[76:79], v[140:143], v[172:175], v[76:79]
	v_mfma_f32_16x16x32_bf16 v[128:131], v[136:139], v[152:155], v[128:131]
	v_mfma_f32_16x16x32_bf16 v[124:127], v[144:147], v[152:155], v[124:127]
	v_mfma_f32_16x16x32_bf16 v[112:115], v[136:139], v[160:163], v[112:115]
	v_mfma_f32_16x16x32_bf16 v[108:111], v[144:147], v[160:163], v[108:111]
	v_mfma_f32_16x16x32_bf16 v[100:103], v[136:139], v[168:171], v[100:103]
	v_mfma_f32_16x16x32_bf16 v[92:95], v[144:147], v[168:171], v[92:95]
	v_mfma_f32_16x16x32_bf16 v[84:87], v[136:139], v[176:179], v[84:87]
	v_mfma_f32_16x16x32_bf16 v[76:79], v[144:147], v[176:179], v[76:79]
	v_mfma_f32_16x16x32_bf16 v[120:123], v[180:183], v[148:151], v[120:123]
	v_mfma_f32_16x16x32_bf16 v[116:119], v[188:191], v[148:151], v[116:119]
	v_mfma_f32_16x16x32_bf16 v[104:107], v[180:183], v[156:159], v[104:107]
	v_mfma_f32_16x16x32_bf16 v[96:99], v[188:191], v[156:159], v[96:99]
	v_mfma_f32_16x16x32_bf16 v[88:91], v[180:183], v[164:167], v[88:91]
	v_mfma_f32_16x16x32_bf16 v[80:83], v[188:191], v[164:167], v[80:83]
	v_mfma_f32_16x16x32_bf16 v[72:75], v[180:183], v[172:175], v[72:75]
	v_mfma_f32_16x16x32_bf16 v[68:71], v[188:191], v[172:175], v[68:71]
	v_mfma_f32_16x16x32_bf16 v[120:123], v[184:187], v[152:155], v[120:123]
	v_mfma_f32_16x16x32_bf16 v[116:119], v[202:205], v[152:155], v[116:119]
	v_mfma_f32_16x16x32_bf16 v[104:107], v[184:187], v[160:163], v[104:107]
	v_mfma_f32_16x16x32_bf16 v[96:99], v[202:205], v[160:163], v[96:99]
	v_mfma_f32_16x16x32_bf16 v[88:91], v[184:187], v[168:171], v[88:91]
	v_mfma_f32_16x16x32_bf16 v[80:83], v[202:205], v[168:171], v[80:83]
	v_mfma_f32_16x16x32_bf16 v[72:75], v[184:187], v[176:179], v[72:75]
	v_mfma_f32_16x16x32_bf16 v[68:71], v[202:205], v[176:179], v[68:71]
	s_barrier
; __device__ __forceinline__ int opaque_tid() { int t = threadIdx.x; asm volatile("" : "+v"(t)); return t; }
; #define PG8_STAGE(bufoff, gbase, voff) do { _Pragma("unroll") for (int _i = 0; _i < 2; ++_i) \
;         __builtin_amdgcn_global_load_lds((const unsigned*)((const char*)(gbase) + (voff)[_i]), (LAS unsigned*)(lds + (bufoff) + ldsw + _i * 8192), 16, 0, 0); } while (0)
; #define PG8_LDA(dst, b, h) do { _Pragma("unroll") for (int m = 0; m < 4; ++m) _Pragma("unroll") for (int k = 0; k < 2; ++k) dst[m][k] = *(const LAS bf16x8*)(lds + PG8_SA(b, h) + aoff + m * 2048 + k * 1024); } while (0)
; #define PG8_MMA(ai, bj, At, Bt) do { __builtin_amdgcn_s_setprio(1); _Pragma("unroll") for (int m = 0; m < 4; ++m) _Pragma("unroll") for (int n = 0; n < 2; ++n) _Pragma("unroll") for (int k = 0; k < 2; ++k) \
;         acc[ai][bj][m][n] = __builtin_amdgcn_mfma_f32_16x16x32_bf16(Bt[n][k], At[m][k], acc[ai][bj][m][n], 0, 0, 0); __builtin_amdgcn_s_setprio(0); } while (0)
; #define PG8_WAIT_V(n) asm volatile("s_waitcnt vmcnt(" #n ")" ::: "memory")
; #define PG8_WAIT_L(n) asm volatile("s_waitcnt lgkmcnt(" #n ")" ::: "memory")
; #define PG8_BAR __builtin_amdgcn_s_barrier()
; #define PG8_SCHED __builtin_amdgcn_sched_barrier(0)
;     __device__ __forceinline__ void operator()(const f32x4 (&acc)[2][2][4][2], const Unit& u, int wr, int wc, int, int) const {
;         const int ol_ = opaque_tid() & 63, fr = ol_ & 15, fq = ol_ >> 4;
;         const int row0 = u.pm * BM + wr * 64 + fr, col0 = u.pn * BM + wc * 32 + 8 * fq;
;         u32x4 cin[2][4][2];
; #pragma unroll
;         for (int ai = 0; ai < 2; ++ai)
; #pragma unroll
;             for (int m = 0; m < 4; ++m)
; #pragma unroll
;                 for (int bj = 0; bj < 2; ++bj) cin[ai][m][bj] = *(const u32x4*)(C + (size_t)(row0 + ai * HALF + m * 16) * ldc + col0 + bj * HALF);
; template <class Epi, class Sched>
; __device__ __forceinline__ void gemm_phase(LAS unsigned char* lds, const Gemm g, const Sched& S, const Epi& E) {
;     ...
;             PG8_LDA(At, 1, 1); PG8_STAGE(PG8_SA(1, 0), a3, voffA);
;             PG8_BAR; PG8_WAIT_L(0); PG8_MMA(1, 0, At, B0); PG8_BAR; PG8_SCHED;
;             PG8_STAGE(PG8_SB(1, 1), b3 + hstepB, voffB);
;             PG8_WAIT_V(6); PG8_BAR; PG8_MMA(1, 1, At, B1); PG8_BAR;
	s_setprio 0
	ds_read_b128 v[148:151], v224 offset:49152
	ds_read_b128 v[152:155], v224 offset:50176
	ds_read_b128 v[156:159], v224 offset:51200
	ds_read_b128 v[160:163], v224 offset:52224
	ds_read_b128 v[164:167], v224 offset:53248
	ds_read_b128 v[168:171], v224 offset:54272
	ds_read_b128 v[172:175], v224 offset:55296
	ds_read_b128 v[176:179], v224 offset:56320
	s_add_i32 s6, s45, s28
	v_lshl_add_u64 v[206:207], v[206:207], 0, s[8:9]
	s_mov_b32 m0, s6
	s_nop 0
	global_load_lds_dwordx4 v[206:207], off
	v_lshl_add_u64 v[206:207], v[208:209], 0, s[8:9]
	s_add_i32 m0, s6, 0x2000
	s_nop 0
	global_load_lds_dwordx4 v[206:207], off
	s_mov_b32 m0, s38
	v_lshl_add_u64 v[206:207], v[210:211], 0, s[8:9]
	global_load_lds_dwordx4 v[206:207], off
	v_lshl_add_u64 v[206:207], v[212:213], 0, s[8:9]
	s_mov_b32 m0, s39
	s_nop 0
	global_load_lds_dwordx4 v[206:207], off
	s_add_u32 s6, s18, 0x160080
	s_addc_u32 s7, s19, 0
	s_add_i32 s18, s20, s28
	s_mov_b32 m0, s18
	s_nop 0
	global_load_lds_dwordx4 v2, s[6:7]
	s_add_i32 m0, s18, 0x2000
	s_nop 0
	global_load_lds_dwordx4 v192, s[6:7]
	s_add_i32 s44, s44, 2
	s_add_u32 s42, s42, 0x100
	s_addc_u32 s43, s43, 0
	s_cmpk_gt_u32 s44, 0x55
	s_mov_b64 s[6:7], s[14:15]
	s_waitcnt lgkmcnt(0)
	s_waitcnt vmcnt(6)
	s_setprio 1
	s_barrier
	v_mfma_f32_16x16x32_bf16 v[64:67], v[132:135], v[148:151], v[64:67]
	v_mfma_f32_16x16x32_bf16 v[60:63], v[140:143], v[148:151], v[60:63]
	v_mfma_f32_16x16x32_bf16 v[52:55], v[132:135], v[156:159], v[52:55]
	v_mfma_f32_16x16x32_bf16 v[44:47], v[140:143], v[156:159], v[44:47]
	v_mfma_f32_16x16x32_bf16 v[36:39], v[132:135], v[164:167], v[36:39]
	v_mfma_f32_16x16x32_bf16 v[28:31], v[140:143], v[164:167], v[28:31]
	v_mfma_f32_16x16x32_bf16 v[20:23], v[132:135], v[172:175], v[20:23]
	v_mfma_f32_16x16x32_bf16 v[12:15], v[140:143], v[172:175], v[12:15]
	v_mfma_f32_16x16x32_bf16 v[64:67], v[136:139], v[152:155], v[64:67]
	v_mfma_f32_16x16x32_bf16 v[60:63], v[144:147], v[152:155], v[60:63]
	v_mfma_f32_16x16x32_bf16 v[52:55], v[136:139], v[160:163], v[52:55]
	v_mfma_f32_16x16x32_bf16 v[44:47], v[144:147], v[160:163], v[44:47]
	v_mfma_f32_16x16x32_bf16 v[36:39], v[136:139], v[168:171], v[36:39]
	v_mfma_f32_16x16x32_bf16 v[28:31], v[144:147], v[168:171], v[28:31]
	v_mfma_f32_16x16x32_bf16 v[20:23], v[136:139], v[176:179], v[20:23]
	v_mfma_f32_16x16x32_bf16 v[12:15], v[144:147], v[176:179], v[12:15]
	v_mfma_f32_16x16x32_bf16 v[56:59], v[180:183], v[148:151], v[56:59]
	v_mfma_f32_16x16x32_bf16 v[48:51], v[188:191], v[148:151], v[48:51]
	v_mfma_f32_16x16x32_bf16 v[40:43], v[180:183], v[156:159], v[40:43]
	v_mfma_f32_16x16x32_bf16 v[32:35], v[188:191], v[156:159], v[32:35]
	v_mfma_f32_16x16x32_bf16 v[24:27], v[180:183], v[164:167], v[24:27]
	v_mfma_f32_16x16x32_bf16 v[16:19], v[188:191], v[164:167], v[16:19]
	v_mfma_f32_16x16x32_bf16 v[8:11], v[180:183], v[172:175], v[8:11]
	v_mfma_f32_16x16x32_bf16 v[4:7], v[188:191], v[172:175], v[4:7]
	v_mfma_f32_16x16x32_bf16 v[56:59], v[184:187], v[152:155], v[56:59]
	v_mfma_f32_16x16x32_bf16 v[48:51], v[202:205], v[152:155], v[48:51]
	v_mfma_f32_16x16x32_bf16 v[40:43], v[184:187], v[160:163], v[40:43]
	v_mfma_f32_16x16x32_bf16 v[32:35], v[202:205], v[160:163], v[32:35]
	v_mfma_f32_16x16x32_bf16 v[24:27], v[184:187], v[168:171], v[24:27]
	v_mfma_f32_16x16x32_bf16 v[16:19], v[202:205], v[168:171], v[16:19]
	v_mfma_f32_16x16x32_bf16 v[8:11], v[184:187], v[176:179], v[8:11]
	v_mfma_f32_16x16x32_bf16 v[4:7], v[202:205], v[176:179], v[4:7]
	s_barrier
	s_cbranch_scc0 .LBB0_1666
	s_setprio 0
	v_mov_b32_e32 v133, v0
	s_lshl_b32 s6, s50, 8
	s_add_i32 s6, s6, s36
	v_and_or_b32 v132, v133, 15, s6
	s_lshl_b32 s6, s49, 8
	v_lshrrev_b32_e32 v133, 1, v133
	v_and_or_b32 v133, v133, 24, s6
	v_or_b32_e32 v134, s37, v133
	v_ashrrev_i32_e32 v135, 31, v134
	v_lshlrev_b64 v[202:203], 1, v[134:135]
	v_ashrrev_i32_e32 v133, 31, v132
	v_lshl_add_u64 v[134:135], s[88:89], 0, v[202:203]
	v_lshlrev_b64 v[226:227], 12, v[132:133]
	v_lshl_add_u64 v[136:137], v[134:135], 0, v[226:227]
	global_load_dwordx4 v[216:219], v[136:137], off
	global_load_dwordx4 v[188:191], v[136:137], off offset:256
	v_or_b32_e32 v136, 16, v132
	v_ashrrev_i32_e32 v137, 31, v136
	v_lshlrev_b64 v[222:223], 12, v[136:137]
	v_lshl_add_u64 v[136:137], v[134:135], 0, v[222:223]
	global_load_dwordx4 v[184:187], v[136:137], off
	global_load_dwordx4 v[180:183], v[136:137], off offset:256
	v_or_b32_e32 v136, 32, v132
	v_ashrrev_i32_e32 v137, 31, v136
	v_lshlrev_b64 v[220:221], 12, v[136:137]
	v_lshl_add_u64 v[136:137], v[134:135], 0, v[220:221]
	global_load_dwordx4 v[176:179], v[136:137], off
	global_load_dwordx4 v[168:171], v[136:137], off offset:256
	v_or_b32_e32 v132, 48, v132
	v_ashrrev_i32_e32 v133, 31, v132
	v_lshlrev_b64 v[212:213], 12, v[132:133]
	v_lshl_add_u64 v[132:133], v[134:135], 0, v[212:213]
	global_load_dwordx4 v[172:175], v[132:133], off
	global_load_dwordx4 v[164:167], v[132:133], off offset:256
	s_mov_b64 s[6:7], 0x80000
	v_lshl_add_u64 v[210:211], v[226:227], 0, s[6:7]
	v_lshl_add_u64 v[132:133], v[134:135], 0, v[210:211]
	global_load_dwordx4 v[160:163], v[132:133], off
	global_load_dwordx4 v[156:159], v[132:133], off offset:256
	s_mov_b64 s[6:7], 0x90000
	v_lshl_add_u64 v[208:209], v[226:227], 0, s[6:7]
	v_lshl_add_u64 v[132:133], v[134:135], 0, v[208:209]
	global_load_dwordx4 v[152:155], v[132:133], off
	global_load_dwordx4 v[148:151], v[132:133], off offset:256
	s_mov_b64 s[6:7], 0xa0000
	v_lshl_add_u64 v[206:207], v[226:227], 0, s[6:7]
	v_lshl_add_u64 v[132:133], v[134:135], 0, v[206:207]
	global_load_dwordx4 v[144:147], v[132:133], off
	global_load_dwordx4 v[140:143], v[132:133], off offset:256
	s_mov_b64 s[6:7], 0xb0000
	v_lshl_add_u64 v[204:205], v[226:227], 0, s[6:7]
	v_lshl_add_u64 v[132:133], v[134:135], 0, v[204:205]
	global_load_dwordx4 v[136:139], v[132:133], off
	s_nop 0
	global_load_dwordx4 v[132:135], v[132:133], off offset:256
	s_and_b64 vcc, exec, s[40:41]
	s_mov_b32 s49, s47
	s_mov_b32 s50, s48
	s_mov_b64 s[14:15], s[4:5]
	s_mov_b64 s[6:7], s[0:1]
	s_waitcnt vmcnt(15)
; __device__ __forceinline__ unsigned cvt_pk_bf16(float lo, float hi) { const f32x2 v = {lo, hi}; const bf16v2_ r = __builtin_convertvector(v, bf16v2_); return __builtin_bit_cast(unsigned, r); }
; __device__ __forceinline__ float bflo(unsigned w) { return __uint_as_float(w << 16); }
; __device__ __forceinline__ float bfhi(unsigned w) { return __uint_as_float(w & 0xffff0000u); }
;     __device__ __forceinline__ void operator()(const f32x4 (&acc)[2][2][4][2], const Unit& u, int wr, int wc, int, int) const {
;     ...
; #pragma unroll
;         for (int ai = 0; ai < 2; ++ai)
; #pragma unroll
;             for (int m = 0; m < 4; ++m)
; #pragma unroll
;                 for (int bj = 0; bj < 2; ++bj) { const u32x4 c = cin[ai][m][bj]; const f32x4 v0 = acc[ai][bj][m][0], v1 = acc[ai][bj][m][1];
;                     u32x4 w; w.x = cvt_pk_bf16(bflo(c.x) + v0[0], bfhi(c.x) + v0[1]); w.y = cvt_pk_bf16(bflo(c.y) + v0[2], bfhi(c.y) + v0[3]);
;                     w.z = cvt_pk_bf16(bflo(c.z) + v1[0], bfhi(c.z) + v1[1]); w.w = cvt_pk_bf16(bflo(c.w) + v1[2], bfhi(c.w) + v1[3]);
;                     *(u32x4*)(C + (size_t)(row0 + ai * HALF + m * 16) * ldc + col0 + bj * HALF) = w; }
	v_lshlrev_b32_e32 v228, 16, v216
	v_and_b32_e32 v229, 0xffff0000, v216
	v_lshlrev_b32_e32 v216, 16, v217
	v_and_b32_e32 v217, 0xffff0000, v217
	v_pk_add_f32 v[128:129], v[128:129], v[228:229]
	v_pk_add_f32 v[130:131], v[130:131], v[216:217]
	v_cvt_pk_bf16_f32 v128, v128, v129
	v_cvt_pk_bf16_f32 v129, v130, v131
	v_lshlrev_b32_e32 v130, 16, v218
	v_and_b32_e32 v131, 0xffff0000, v218
	v_pk_add_f32 v[124:125], v[124:125], v[130:131]
	s_nop 0
	v_cvt_pk_bf16_f32 v130, v124, v125
	v_lshlrev_b32_e32 v124, 16, v219
	v_and_b32_e32 v125, 0xffff0000, v219
	v_pk_add_f32 v[124:125], v[126:127], v[124:125]
	s_waitcnt vmcnt(14)
	v_lshlrev_b32_e32 v126, 16, v188
	v_and_b32_e32 v127, 0xffff0000, v188
	v_pk_add_f32 v[120:121], v[120:121], v[126:127]
	v_lshlrev_b32_e32 v126, 16, v189
	v_and_b32_e32 v127, 0xffff0000, v189
	v_pk_add_f32 v[122:123], v[122:123], v[126:127]
	v_cvt_pk_bf16_f32 v120, v120, v121
	v_cvt_pk_bf16_f32 v121, v122, v123
	v_lshlrev_b32_e32 v122, 16, v190
	v_and_b32_e32 v123, 0xffff0000, v190
	v_pk_add_f32 v[116:117], v[116:117], v[122:123]
	v_cvt_pk_bf16_f32 v131, v124, v125
	v_cvt_pk_bf16_f32 v122, v116, v117
	v_lshlrev_b32_e32 v116, 16, v191
	v_and_b32_e32 v117, 0xffff0000, v191
	v_pk_add_f32 v[116:117], v[118:119], v[116:117]
	v_lshl_add_u64 v[124:125], s[88:89], 0, v[226:227]
	v_cvt_pk_bf16_f32 v123, v116, v117
	s_waitcnt vmcnt(13)
	v_lshlrev_b32_e32 v116, 16, v184
	v_and_b32_e32 v117, 0xffff0000, v184
	v_pk_add_f32 v[112:113], v[112:113], v[116:117]
	v_lshlrev_b32_e32 v116, 16, v185
	v_and_b32_e32 v117, 0xffff0000, v185
	v_pk_add_f32 v[114:115], v[114:115], v[116:117]
	v_cvt_pk_bf16_f32 v112, v112, v113
	v_cvt_pk_bf16_f32 v113, v114, v115
	v_lshlrev_b32_e32 v114, 16, v186
	v_and_b32_e32 v115, 0xffff0000, v186
	v_pk_add_f32 v[108:109], v[108:109], v[114:115]
	v_lshl_add_u64 v[124:125], v[124:125], 0, v[202:203]
	v_cvt_pk_bf16_f32 v114, v108, v109
	v_lshlrev_b32_e32 v108, 16, v187
	v_and_b32_e32 v109, 0xffff0000, v187
	v_pk_add_f32 v[108:109], v[110:111], v[108:109]
	s_waitcnt vmcnt(12)
	v_lshlrev_b32_e32 v110, 16, v180
	v_and_b32_e32 v111, 0xffff0000, v180
	v_pk_add_f32 v[104:105], v[104:105], v[110:111]
	v_lshlrev_b32_e32 v110, 16, v181
	v_and_b32_e32 v111, 0xffff0000, v181
	v_pk_add_f32 v[106:107], v[106:107], v[110:111]
	v_cvt_pk_bf16_f32 v104, v104, v105
	v_cvt_pk_bf16_f32 v105, v106, v107
	v_lshlrev_b32_e32 v106, 16, v182
	v_and_b32_e32 v107, 0xffff0000, v182
	v_pk_add_f32 v[96:97], v[96:97], v[106:107]
	v_cvt_pk_bf16_f32 v115, v108, v109
	v_cvt_pk_bf16_f32 v106, v96, v97
	v_lshlrev_b32_e32 v96, 16, v183
	v_and_b32_e32 v97, 0xffff0000, v183
	v_pk_add_f32 v[96:97], v[98:99], v[96:97]
	s_waitcnt vmcnt(11)
	v_lshlrev_b32_e32 v98, 16, v177
	v_cvt_pk_bf16_f32 v107, v96, v97
	v_lshlrev_b32_e32 v96, 16, v176
	v_and_b32_e32 v97, 0xffff0000, v176
	v_and_b32_e32 v99, 0xffff0000, v177
	v_pk_add_f32 v[96:97], v[100:101], v[96:97]
	v_pk_add_f32 v[98:99], v[102:103], v[98:99]
	v_cvt_pk_bf16_f32 v96, v96, v97
	v_cvt_pk_bf16_f32 v97, v98, v99
	v_lshlrev_b32_e32 v98, 16, v178
	v_and_b32_e32 v99, 0xffff0000, v178
	v_pk_add_f32 v[92:93], v[92:93], v[98:99]
	v_lshl_add_u64 v[108:109], s[88:89], 0, v[222:223]
	v_cvt_pk_bf16_f32 v98, v92, v93
	v_lshlrev_b32_e32 v92, 16, v179
	v_and_b32_e32 v93, 0xffff0000, v179
	v_pk_add_f32 v[92:93], v[94:95], v[92:93]
	s_waitcnt vmcnt(10)
	v_lshlrev_b32_e32 v94, 16, v168
	v_and_b32_e32 v95, 0xffff0000, v168
	v_pk_add_f32 v[88:89], v[88:89], v[94:95]
	v_lshlrev_b32_e32 v94, 16, v169
	v_and_b32_e32 v95, 0xffff0000, v169
	v_pk_add_f32 v[90:91], v[90:91], v[94:95]
	v_cvt_pk_bf16_f32 v88, v88, v89
	v_cvt_pk_bf16_f32 v89, v90, v91
	v_lshlrev_b32_e32 v90, 16, v170
	v_and_b32_e32 v91, 0xffff0000, v170
	v_pk_add_f32 v[80:81], v[80:81], v[90:91]
	v_cvt_pk_bf16_f32 v99, v92, v93
	v_cvt_pk_bf16_f32 v90, v80, v81
	v_lshlrev_b32_e32 v80, 16, v171
	v_and_b32_e32 v81, 0xffff0000, v171
	v_pk_add_f32 v[80:81], v[82:83], v[80:81]
	s_waitcnt vmcnt(9)
	v_lshlrev_b32_e32 v82, 16, v173
	v_cvt_pk_bf16_f32 v91, v80, v81
	v_lshlrev_b32_e32 v80, 16, v172
	v_and_b32_e32 v81, 0xffff0000, v172
	v_and_b32_e32 v83, 0xffff0000, v173
	v_pk_add_f32 v[80:81], v[84:85], v[80:81]
	v_pk_add_f32 v[82:83], v[86:87], v[82:83]
	v_cvt_pk_bf16_f32 v80, v80, v81
	v_cvt_pk_bf16_f32 v81, v82, v83
	v_lshlrev_b32_e32 v82, 16, v174
	v_and_b32_e32 v83, 0xffff0000, v174
	v_pk_add_f32 v[76:77], v[76:77], v[82:83]
	v_lshl_add_u64 v[92:93], s[88:89], 0, v[220:221]
	v_cvt_pk_bf16_f32 v82, v76, v77
	v_lshlrev_b32_e32 v76, 16, v175
	v_and_b32_e32 v77, 0xffff0000, v175
	v_pk_add_f32 v[76:77], v[78:79], v[76:77]
	s_waitcnt vmcnt(8)
	v_lshlrev_b32_e32 v78, 16, v164
	v_and_b32_e32 v79, 0xffff0000, v164
	v_pk_add_f32 v[72:73], v[72:73], v[78:79]
	v_lshlrev_b32_e32 v78, 16, v165
	v_and_b32_e32 v79, 0xffff0000, v165
	v_pk_add_f32 v[74:75], v[74:75], v[78:79]
	v_cvt_pk_bf16_f32 v72, v72, v73
	v_cvt_pk_bf16_f32 v73, v74, v75
	v_lshlrev_b32_e32 v74, 16, v166
	v_and_b32_e32 v75, 0xffff0000, v166
	v_pk_add_f32 v[68:69], v[68:69], v[74:75]
	v_cvt_pk_bf16_f32 v83, v76, v77
	v_cvt_pk_bf16_f32 v74, v68, v69
	v_lshlrev_b32_e32 v68, 16, v167
	v_and_b32_e32 v69, 0xffff0000, v167
	v_pk_add_f32 v[68:69], v[70:71], v[68:69]
	v_lshl_add_u64 v[76:77], s[88:89], 0, v[212:213]
	v_cvt_pk_bf16_f32 v75, v68, v69
	s_waitcnt vmcnt(7)
	v_lshlrev_b32_e32 v68, 16, v160
	v_and_b32_e32 v69, 0xffff0000, v160
	v_pk_add_f32 v[64:65], v[64:65], v[68:69]
	v_lshlrev_b32_e32 v68, 16, v161
	v_and_b32_e32 v69, 0xffff0000, v161
	v_pk_add_f32 v[66:67], v[66:67], v[68:69]
	v_cvt_pk_bf16_f32 v64, v64, v65
	v_cvt_pk_bf16_f32 v65, v66, v67
	v_lshlrev_b32_e32 v66, 16, v162
	v_and_b32_e32 v67, 0xffff0000, v162
	v_pk_add_f32 v[60:61], v[60:61], v[66:67]
	v_lshl_add_u64 v[108:109], v[108:109], 0, v[202:203]
	v_cvt_pk_bf16_f32 v66, v60, v61
	v_lshlrev_b32_e32 v60, 16, v163
	v_and_b32_e32 v61, 0xffff0000, v163
	v_pk_add_f32 v[60:61], v[62:63], v[60:61]
	s_waitcnt vmcnt(6)
; __device__ __forceinline__ unsigned cvt_pk_bf16(float lo, float hi) { const f32x2 v = {lo, hi}; const bf16v2_ r = __builtin_convertvector(v, bf16v2_); return __builtin_bit_cast(unsigned, r); }
; __device__ __forceinline__ float bflo(unsigned w) { return __uint_as_float(w << 16); }
; __device__ __forceinline__ float bfhi(unsigned w) { return __uint_as_float(w & 0xffff0000u); }
; #define PG8_WAIT_V(n) asm volatile("s_waitcnt vmcnt(" #n ")" ::: "memory")
; #define PG8_BAR __builtin_amdgcn_s_barrier()
;     __device__ __forceinline__ void operator()(const f32x4 (&acc)[2][2][4][2], const Unit& u, int wr, int wc, int, int) const {
;     ...
;                 for (int bj = 0; bj < 2; ++bj) { const u32x4 c = cin[ai][m][bj]; const f32x4 v0 = acc[ai][bj][m][0], v1 = acc[ai][bj][m][1];
;                     u32x4 w; w.x = cvt_pk_bf16(bflo(c.x) + v0[0], bfhi(c.x) + v0[1]); w.y = cvt_pk_bf16(bflo(c.y) + v0[2], bfhi(c.y) + v0[3]);
;                     w.z = cvt_pk_bf16(bflo(c.z) + v1[0], bfhi(c.z) + v1[1]); w.w = cvt_pk_bf16(bflo(c.w) + v1[2], bfhi(c.w) + v1[3]);
;                     *(u32x4*)(C + (size_t)(row0 + ai * HALF + m * 16) * ldc + col0 + bj * HALF) = w; }
; template <class Epi, class Sched>
; __device__ __forceinline__ void gemm_phase(LAS unsigned char* lds, const Gemm g, const Sched& S, const Epi& E) {
;     ...
;     PG8_WAIT_V(0);
;     if (wr == 0) PG8_BAR;
;     PG8_BAR;
	v_lshlrev_b32_e32 v62, 16, v156
	v_and_b32_e32 v63, 0xffff0000, v156
	v_pk_add_f32 v[56:57], v[56:57], v[62:63]
	v_lshlrev_b32_e32 v62, 16, v157
	v_and_b32_e32 v63, 0xffff0000, v157
	v_pk_add_f32 v[58:59], v[58:59], v[62:63]
	v_cvt_pk_bf16_f32 v56, v56, v57
	v_cvt_pk_bf16_f32 v57, v58, v59
	v_lshlrev_b32_e32 v58, 16, v158
	v_and_b32_e32 v59, 0xffff0000, v158
	v_pk_add_f32 v[48:49], v[48:49], v[58:59]
	v_cvt_pk_bf16_f32 v67, v60, v61
	v_cvt_pk_bf16_f32 v58, v48, v49
	v_lshlrev_b32_e32 v48, 16, v159
	v_and_b32_e32 v49, 0xffff0000, v159
	v_pk_add_f32 v[48:49], v[50:51], v[48:49]
	s_waitcnt vmcnt(5)
	v_lshlrev_b32_e32 v50, 16, v153
	v_cvt_pk_bf16_f32 v59, v48, v49
	v_lshlrev_b32_e32 v48, 16, v152
	v_and_b32_e32 v49, 0xffff0000, v152
	v_and_b32_e32 v51, 0xffff0000, v153
	v_pk_add_f32 v[48:49], v[52:53], v[48:49]
	v_pk_add_f32 v[50:51], v[54:55], v[50:51]
	v_cvt_pk_bf16_f32 v48, v48, v49
	v_cvt_pk_bf16_f32 v49, v50, v51
	v_lshlrev_b32_e32 v50, 16, v154
	v_and_b32_e32 v51, 0xffff0000, v154
	v_pk_add_f32 v[44:45], v[44:45], v[50:51]
	v_lshl_add_u64 v[60:61], s[88:89], 0, v[210:211]
	v_cvt_pk_bf16_f32 v50, v44, v45
	v_lshlrev_b32_e32 v44, 16, v155
	v_and_b32_e32 v45, 0xffff0000, v155
	v_pk_add_f32 v[44:45], v[46:47], v[44:45]
	s_waitcnt vmcnt(4)
	v_lshlrev_b32_e32 v46, 16, v148
	v_and_b32_e32 v47, 0xffff0000, v148
	v_pk_add_f32 v[40:41], v[40:41], v[46:47]
	v_lshlrev_b32_e32 v46, 16, v149
	v_and_b32_e32 v47, 0xffff0000, v149
	v_pk_add_f32 v[42:43], v[42:43], v[46:47]
	v_cvt_pk_bf16_f32 v40, v40, v41
	v_cvt_pk_bf16_f32 v41, v42, v43
	v_lshlrev_b32_e32 v42, 16, v150
	v_and_b32_e32 v43, 0xffff0000, v150
	v_pk_add_f32 v[32:33], v[32:33], v[42:43]
	v_cvt_pk_bf16_f32 v51, v44, v45
	v_cvt_pk_bf16_f32 v42, v32, v33
	v_lshlrev_b32_e32 v32, 16, v151
	v_and_b32_e32 v33, 0xffff0000, v151
	v_pk_add_f32 v[32:33], v[34:35], v[32:33]
	s_waitcnt vmcnt(3)
	v_lshlrev_b32_e32 v34, 16, v145
	v_cvt_pk_bf16_f32 v43, v32, v33
	v_lshlrev_b32_e32 v32, 16, v144
	v_and_b32_e32 v33, 0xffff0000, v144
	v_and_b32_e32 v35, 0xffff0000, v145
	v_pk_add_f32 v[32:33], v[36:37], v[32:33]
	v_pk_add_f32 v[34:35], v[38:39], v[34:35]
	v_cvt_pk_bf16_f32 v32, v32, v33
	v_cvt_pk_bf16_f32 v33, v34, v35
	v_lshlrev_b32_e32 v34, 16, v146
	v_and_b32_e32 v35, 0xffff0000, v146
	v_pk_add_f32 v[28:29], v[28:29], v[34:35]
	v_lshl_add_u64 v[44:45], s[88:89], 0, v[208:209]
	v_cvt_pk_bf16_f32 v34, v28, v29
	v_lshlrev_b32_e32 v28, 16, v147
	v_and_b32_e32 v29, 0xffff0000, v147
	v_pk_add_f32 v[28:29], v[30:31], v[28:29]
	s_waitcnt vmcnt(2)
	v_lshlrev_b32_e32 v30, 16, v140
	v_and_b32_e32 v31, 0xffff0000, v140
	v_pk_add_f32 v[24:25], v[24:25], v[30:31]
	v_lshlrev_b32_e32 v30, 16, v141
	v_and_b32_e32 v31, 0xffff0000, v141
	v_pk_add_f32 v[26:27], v[26:27], v[30:31]
	v_cvt_pk_bf16_f32 v24, v24, v25
	v_cvt_pk_bf16_f32 v25, v26, v27
	v_lshlrev_b32_e32 v26, 16, v142
	v_and_b32_e32 v27, 0xffff0000, v142
	v_pk_add_f32 v[16:17], v[16:17], v[26:27]
	v_cvt_pk_bf16_f32 v35, v28, v29
	v_cvt_pk_bf16_f32 v26, v16, v17
	v_lshlrev_b32_e32 v16, 16, v143
	v_and_b32_e32 v17, 0xffff0000, v143
	v_pk_add_f32 v[16:17], v[18:19], v[16:17]
	s_waitcnt vmcnt(1)
	v_lshlrev_b32_e32 v18, 16, v137
	v_cvt_pk_bf16_f32 v27, v16, v17
	v_lshlrev_b32_e32 v16, 16, v136
	v_and_b32_e32 v17, 0xffff0000, v136
	v_and_b32_e32 v19, 0xffff0000, v137
	v_pk_add_f32 v[16:17], v[20:21], v[16:17]
	v_pk_add_f32 v[18:19], v[22:23], v[18:19]
	v_cvt_pk_bf16_f32 v16, v16, v17
	v_cvt_pk_bf16_f32 v17, v18, v19
	v_lshlrev_b32_e32 v18, 16, v138
	v_and_b32_e32 v19, 0xffff0000, v138
	v_pk_add_f32 v[12:13], v[12:13], v[18:19]
	v_lshl_add_u64 v[28:29], s[88:89], 0, v[206:207]
	v_cvt_pk_bf16_f32 v18, v12, v13
	v_lshlrev_b32_e32 v12, 16, v139
	v_and_b32_e32 v13, 0xffff0000, v139
	v_pk_add_f32 v[12:13], v[14:15], v[12:13]
	s_waitcnt vmcnt(0)
	v_lshlrev_b32_e32 v14, 16, v132
	v_and_b32_e32 v15, 0xffff0000, v132
	v_pk_add_f32 v[8:9], v[8:9], v[14:15]
	v_lshlrev_b32_e32 v14, 16, v133
	v_and_b32_e32 v15, 0xffff0000, v133
	v_pk_add_f32 v[10:11], v[10:11], v[14:15]
	v_cvt_pk_bf16_f32 v8, v8, v9
	v_cvt_pk_bf16_f32 v9, v10, v11
	v_lshlrev_b32_e32 v10, 16, v134
	v_and_b32_e32 v11, 0xffff0000, v134
	v_pk_add_f32 v[4:5], v[4:5], v[10:11]
	v_cvt_pk_bf16_f32 v19, v12, v13
	v_cvt_pk_bf16_f32 v10, v4, v5
	v_lshlrev_b32_e32 v4, 16, v135
	v_and_b32_e32 v5, 0xffff0000, v135
	v_lshl_add_u64 v[12:13], s[88:89], 0, v[204:205]
	v_pk_add_f32 v[4:5], v[6:7], v[4:5]
	v_lshl_add_u64 v[92:93], v[92:93], 0, v[202:203]
	v_lshl_add_u64 v[76:77], v[76:77], 0, v[202:203]
	v_lshl_add_u64 v[60:61], v[60:61], 0, v[202:203]
	v_lshl_add_u64 v[44:45], v[44:45], 0, v[202:203]
	v_lshl_add_u64 v[28:29], v[28:29], 0, v[202:203]
	v_lshl_add_u64 v[12:13], v[12:13], 0, v[202:203]
	v_cvt_pk_bf16_f32 v11, v4, v5
	global_store_dwordx4 v[124:125], v[128:131], off
	global_store_dwordx4 v[124:125], v[120:123], off offset:256
	global_store_dwordx4 v[108:109], v[112:115], off
	global_store_dwordx4 v[108:109], v[104:107], off offset:256
	global_store_dwordx4 v[92:93], v[96:99], off
	global_store_dwordx4 v[92:93], v[88:91], off offset:256
	global_store_dwordx4 v[76:77], v[80:83], off
	global_store_dwordx4 v[76:77], v[72:75], off offset:256
	global_store_dwordx4 v[60:61], v[64:67], off
	global_store_dwordx4 v[60:61], v[56:59], off offset:256
	global_store_dwordx4 v[44:45], v[48:51], off
	global_store_dwordx4 v[44:45], v[40:43], off offset:256
	global_store_dwordx4 v[28:29], v[32:35], off
	global_store_dwordx4 v[28:29], v[24:27], off offset:256
	global_store_dwordx4 v[12:13], v[16:19], off
	global_store_dwordx4 v[12:13], v[8:11], off offset:256
	s_cbranch_vccz .LBB0_1655
	s_waitcnt vmcnt(0)
	s_cmpk_gt_u32 s2, 0xff
	s_cbranch_scc1 .LBB0_1670
	s_barrier
